# GEMM K-loops: back edge rotated (loop-head scalar block and counter updates issued before the closing barrier)
# baseline (speedup 1.0000x reference)
.Lrot_lbb0_98:
	ds_read_b128 v[144:147], v143
	ds_read_b128 v[148:151], v143 offset:1024
	ds_read_b128 v[152:155], v143 offset:2048
	ds_read_b128 v[156:159], v143 offset:3072
	v_add_u32_e32 v143, s41, v140
	ds_read_b128 v[164:167], v143
	ds_read_b128 v[168:171], v143 offset:1024
	ds_read_b128 v[172:175], v143 offset:2048
	ds_read_b128 v[176:179], v143 offset:3072
	v_lshl_add_u64 v[204:205], s[48:49], 0, v[134:135]
	s_add_i32 m0, s22, 0xc000
	ds_read_b128 v[180:183], v142
	ds_read_b128 v[184:187], v142 offset:1024
	ds_read_b128 v[188:191], v142 offset:2048
	ds_read_b128 v[192:195], v142 offset:3072
	ds_read_b128 v[212:215], v142 offset:4096
	ds_read_b128 v[216:219], v142 offset:5120
	ds_read_b128 v[220:223], v142 offset:6144
	ds_read_b128 v[232:235], v142 offset:7168
	global_load_lds_dwordx4 v[204:205], off
	v_lshl_add_u64 v[204:205], s[48:49], 0, v[136:137]
	s_add_i32 m0, s22, 0xe000
	s_nop 0
	global_load_lds_dwordx4 v[204:205], off
	s_waitcnt vmcnt(8)
	s_waitcnt lgkmcnt(0)
	s_barrier
	s_waitcnt lgkmcnt(0)
	v_mfma_f32_16x16x32_bf16 v[124:127], v[144:147], v[180:183], v[124:127]
	v_mfma_f32_16x16x32_bf16 v[120:123], v[152:155], v[180:183], v[120:123]
	v_mfma_f32_16x16x32_bf16 v[116:119], v[144:147], v[188:191], v[116:119]
	v_mfma_f32_16x16x32_bf16 v[108:111], v[152:155], v[188:191], v[108:111]
	v_mfma_f32_16x16x32_bf16 v[100:103], v[144:147], v[212:215], v[100:103]
	v_mfma_f32_16x16x32_bf16 v[92:95], v[152:155], v[212:215], v[92:95]
	v_mfma_f32_16x16x32_bf16 v[84:87], v[144:147], v[220:223], v[84:87]
	v_mfma_f32_16x16x32_bf16 v[76:79], v[152:155], v[220:223], v[76:79]
	v_mfma_f32_16x16x32_bf16 v[124:127], v[148:151], v[184:187], v[124:127]
	v_mfma_f32_16x16x32_bf16 v[120:123], v[156:159], v[184:187], v[120:123]
	v_mfma_f32_16x16x32_bf16 v[116:119], v[148:151], v[192:195], v[116:119]
	v_mfma_f32_16x16x32_bf16 v[108:111], v[156:159], v[192:195], v[108:111]
	v_mfma_f32_16x16x32_bf16 v[100:103], v[148:151], v[216:219], v[100:103]
	v_mfma_f32_16x16x32_bf16 v[92:95], v[156:159], v[216:219], v[92:95]
	v_mfma_f32_16x16x32_bf16 v[84:87], v[148:151], v[232:235], v[84:87]
	v_mfma_f32_16x16x32_bf16 v[76:79], v[156:159], v[232:235], v[76:79]
	v_mfma_f32_16x16x32_bf16 v[112:115], v[164:167], v[180:183], v[112:115]
	v_mfma_f32_16x16x32_bf16 v[104:107], v[172:175], v[180:183], v[104:107]
	v_mfma_f32_16x16x32_bf16 v[96:99], v[164:167], v[188:191], v[96:99]
	v_mfma_f32_16x16x32_bf16 v[88:91], v[172:175], v[188:191], v[88:91]
	v_mfma_f32_16x16x32_bf16 v[80:83], v[164:167], v[212:215], v[80:83]
	v_mfma_f32_16x16x32_bf16 v[72:75], v[172:175], v[212:215], v[72:75]
	v_mfma_f32_16x16x32_bf16 v[68:71], v[164:167], v[220:223], v[68:71]
	v_mfma_f32_16x16x32_bf16 v[64:67], v[172:175], v[220:223], v[64:67]
	v_mfma_f32_16x16x32_bf16 v[112:115], v[168:171], v[184:187], v[112:115]
	v_mfma_f32_16x16x32_bf16 v[104:107], v[176:179], v[184:187], v[104:107]
	v_mfma_f32_16x16x32_bf16 v[96:99], v[168:171], v[192:195], v[96:99]
	v_mfma_f32_16x16x32_bf16 v[88:91], v[176:179], v[192:195], v[88:91]
	v_mfma_f32_16x16x32_bf16 v[80:83], v[168:171], v[216:219], v[80:83]
	v_mfma_f32_16x16x32_bf16 v[72:75], v[176:179], v[216:219], v[72:75]
	v_mfma_f32_16x16x32_bf16 v[68:71], v[168:171], v[232:235], v[68:71]
	v_mfma_f32_16x16x32_bf16 v[64:67], v[176:179], v[232:235], v[64:67]
	s_barrier
	s_add_i32 s47, s54, s20
	v_lshl_add_u64 v[204:205], s[50:51], 0, v[196:197]
	s_mov_b32 m0, s47
	ds_read_b128 v[180:183], v142 offset:16384
	ds_read_b128 v[184:187], v142 offset:17408
	ds_read_b128 v[188:191], v142 offset:18432
	ds_read_b128 v[192:195], v142 offset:19456
	ds_read_b128 v[212:215], v142 offset:20480
	ds_read_b128 v[216:219], v142 offset:21504
	ds_read_b128 v[220:223], v142 offset:22528
	ds_read_b128 v[232:235], v142 offset:23552
	global_load_lds_dwordx4 v[204:205], off
	s_add_i32 m0, s47, 0x2000
	s_add_u32 s54, s50, 0x40000
	v_lshl_add_u64 v[206:207], s[50:51], 0, v[128:129]
	s_addc_u32 s55, s51, 0
	s_add_i32 s41, s41, s20
	global_load_lds_dwordx4 v[206:207], off
	v_lshl_add_u64 v[236:237], s[54:55], 0, v[196:197]
	s_mov_b32 m0, s41
	v_lshl_add_u64 v[238:239], s[52:53], 0, v[130:131]
	global_load_lds_dwordx4 v[236:237], off
	v_lshl_add_u64 v[236:237], s[54:55], 0, v[128:129]
	s_add_i32 m0, s41, 0x2000
	s_nop 0
	global_load_lds_dwordx4 v[236:237], off
	v_lshl_add_u64 v[236:237], s[52:53], 0, v[132:133]
	s_mov_b32 m0, s22
	s_nop 0
	global_load_lds_dwordx4 v[236:237], off
	s_mov_b32 m0, s23
	s_nop 0
	global_load_lds_dwordx4 v[238:239], off
	s_waitcnt vmcnt(8)
	s_waitcnt lgkmcnt(0)
	s_barrier
	s_waitcnt lgkmcnt(0)
	v_mfma_f32_16x16x32_bf16 v[60:63], v[144:147], v[180:183], v[60:63]
	v_mfma_f32_16x16x32_bf16 v[56:59], v[152:155], v[180:183], v[56:59]
	v_mfma_f32_16x16x32_bf16 v[52:55], v[144:147], v[188:191], v[52:55]
	v_mfma_f32_16x16x32_bf16 v[44:47], v[152:155], v[188:191], v[44:47]
	v_mfma_f32_16x16x32_bf16 v[36:39], v[144:147], v[212:215], v[36:39]
	v_mfma_f32_16x16x32_bf16 v[28:31], v[152:155], v[212:215], v[28:31]
	v_mfma_f32_16x16x32_bf16 v[20:23], v[144:147], v[220:223], v[20:23]
	v_mfma_f32_16x16x32_bf16 v[12:15], v[152:155], v[220:223], v[12:15]
	v_mfma_f32_16x16x32_bf16 v[60:63], v[148:151], v[184:187], v[60:63]
	v_mfma_f32_16x16x32_bf16 v[56:59], v[156:159], v[184:187], v[56:59]
	v_mfma_f32_16x16x32_bf16 v[52:55], v[148:151], v[192:195], v[52:55]
	v_mfma_f32_16x16x32_bf16 v[44:47], v[156:159], v[192:195], v[44:47]
	v_mfma_f32_16x16x32_bf16 v[36:39], v[148:151], v[216:219], v[36:39]
	v_mfma_f32_16x16x32_bf16 v[28:31], v[156:159], v[216:219], v[28:31]
	v_mfma_f32_16x16x32_bf16 v[20:23], v[148:151], v[232:235], v[20:23]
	v_mfma_f32_16x16x32_bf16 v[12:15], v[156:159], v[232:235], v[12:15]
	v_mfma_f32_16x16x32_bf16 v[48:51], v[164:167], v[180:183], v[48:51]
	v_mfma_f32_16x16x32_bf16 v[40:43], v[172:175], v[180:183], v[40:43]
	v_mfma_f32_16x16x32_bf16 v[32:35], v[164:167], v[188:191], v[32:35]
	v_mfma_f32_16x16x32_bf16 v[24:27], v[172:175], v[188:191], v[24:27]
	v_mfma_f32_16x16x32_bf16 v[16:19], v[164:167], v[212:215], v[16:19]
	v_mfma_f32_16x16x32_bf16 v[8:11], v[172:175], v[212:215], v[8:11]
	v_mfma_f32_16x16x32_bf16 v[4:7], v[164:167], v[220:223], v[4:7]
	v_mfma_f32_16x16x32_bf16 v[0:3], v[172:175], v[220:223], v[0:3]
	v_mfma_f32_16x16x32_bf16 v[48:51], v[168:171], v[184:187], v[48:51]
	v_mfma_f32_16x16x32_bf16 v[40:43], v[176:179], v[184:187], v[40:43]
	v_mfma_f32_16x16x32_bf16 v[32:35], v[168:171], v[192:195], v[32:35]
	v_mfma_f32_16x16x32_bf16 v[24:27], v[176:179], v[192:195], v[24:27]
	v_mfma_f32_16x16x32_bf16 v[16:19], v[168:171], v[216:219], v[16:19]
	v_mfma_f32_16x16x32_bf16 v[8:11], v[176:179], v[216:219], v[8:11]
	v_mfma_f32_16x16x32_bf16 v[4:7], v[168:171], v[232:235], v[4:7]
	v_mfma_f32_16x16x32_bf16 v[0:3], v[176:179], v[232:235], v[0:3]
	s_barrier
	s_add_i32 s41, 0, 0x18000
	v_add_u32_e32 v143, s41, v140
	s_add_i32 s47, 0, 0x1c000
	ds_read_b128 v[144:147], v143
	ds_read_b128 v[148:151], v143 offset:1024
	ds_read_b128 v[152:155], v143 offset:2048
	ds_read_b128 v[156:159], v143 offset:3072
	v_add_u32_e32 v143, s47, v140
	ds_read_b128 v[164:167], v143
	ds_read_b128 v[168:171], v143 offset:1024
	ds_read_b128 v[172:175], v143 offset:2048
	ds_read_b128 v[176:179], v143 offset:3072
	s_add_u32 s52, s52, 0x40000
	s_addc_u32 s53, s53, 0
	s_mov_b32 m0, s24
	v_lshl_add_u64 v[240:241], s[52:53], 0, v[132:133]
	ds_read_b128 v[180:183], v142 offset:32768
	ds_read_b128 v[184:187], v142 offset:33792
	ds_read_b128 v[188:191], v142 offset:34816
	ds_read_b128 v[192:195], v142 offset:35840
	ds_read_b128 v[212:215], v142 offset:36864
	ds_read_b128 v[216:219], v142 offset:37888
	ds_read_b128 v[220:223], v142 offset:38912
	ds_read_b128 v[232:235], v142 offset:39936
	global_load_lds_dwordx4 v[240:241], off
	v_lshl_add_u64 v[240:241], s[52:53], 0, v[130:131]
	s_mov_b32 m0, s25
	s_nop 0
	global_load_lds_dwordx4 v[240:241], off
	s_waitcnt vmcnt(8)
	s_waitcnt lgkmcnt(0)
	s_barrier
	s_waitcnt lgkmcnt(0)
	v_mfma_f32_16x16x32_bf16 v[124:127], v[144:147], v[180:183], v[124:127]
	v_mfma_f32_16x16x32_bf16 v[120:123], v[152:155], v[180:183], v[120:123]
	v_mfma_f32_16x16x32_bf16 v[116:119], v[144:147], v[188:191], v[116:119]
	v_mfma_f32_16x16x32_bf16 v[108:111], v[152:155], v[188:191], v[108:111]
	v_mfma_f32_16x16x32_bf16 v[100:103], v[144:147], v[212:215], v[100:103]
	v_mfma_f32_16x16x32_bf16 v[92:95], v[152:155], v[212:215], v[92:95]
	v_mfma_f32_16x16x32_bf16 v[84:87], v[144:147], v[220:223], v[84:87]
	v_mfma_f32_16x16x32_bf16 v[76:79], v[152:155], v[220:223], v[76:79]
	v_mfma_f32_16x16x32_bf16 v[124:127], v[148:151], v[184:187], v[124:127]
	v_mfma_f32_16x16x32_bf16 v[120:123], v[156:159], v[184:187], v[120:123]
	v_mfma_f32_16x16x32_bf16 v[116:119], v[148:151], v[192:195], v[116:119]
	v_mfma_f32_16x16x32_bf16 v[108:111], v[156:159], v[192:195], v[108:111]
	v_mfma_f32_16x16x32_bf16 v[100:103], v[148:151], v[216:219], v[100:103]
	v_mfma_f32_16x16x32_bf16 v[92:95], v[156:159], v[216:219], v[92:95]
	v_mfma_f32_16x16x32_bf16 v[84:87], v[148:151], v[232:235], v[84:87]
	v_mfma_f32_16x16x32_bf16 v[76:79], v[156:159], v[232:235], v[76:79]
	v_mfma_f32_16x16x32_bf16 v[112:115], v[164:167], v[180:183], v[112:115]
	v_mfma_f32_16x16x32_bf16 v[104:107], v[172:175], v[180:183], v[104:107]
	v_mfma_f32_16x16x32_bf16 v[96:99], v[164:167], v[188:191], v[96:99]
	v_mfma_f32_16x16x32_bf16 v[88:91], v[172:175], v[188:191], v[88:91]
	v_mfma_f32_16x16x32_bf16 v[80:83], v[164:167], v[212:215], v[80:83]
	v_mfma_f32_16x16x32_bf16 v[72:75], v[172:175], v[212:215], v[72:75]
	v_mfma_f32_16x16x32_bf16 v[68:71], v[164:167], v[220:223], v[68:71]
	v_mfma_f32_16x16x32_bf16 v[64:67], v[172:175], v[220:223], v[64:67]
	v_mfma_f32_16x16x32_bf16 v[112:115], v[168:171], v[184:187], v[112:115]
	v_mfma_f32_16x16x32_bf16 v[104:107], v[176:179], v[184:187], v[104:107]
	v_mfma_f32_16x16x32_bf16 v[96:99], v[168:171], v[192:195], v[96:99]
	v_mfma_f32_16x16x32_bf16 v[88:91], v[176:179], v[192:195], v[88:91]
	v_mfma_f32_16x16x32_bf16 v[80:83], v[168:171], v[216:219], v[80:83]
	v_mfma_f32_16x16x32_bf16 v[72:75], v[176:179], v[216:219], v[72:75]
	v_mfma_f32_16x16x32_bf16 v[68:71], v[168:171], v[232:235], v[68:71]
	v_mfma_f32_16x16x32_bf16 v[64:67], v[176:179], v[232:235], v[64:67]
	s_barrier
	s_add_i32 s41, s41, s20
	v_lshl_add_u64 v[204:205], v[204:205], 0, s[10:11]
	s_mov_b32 m0, s41
	ds_read_b128 v[180:183], v142 offset:49152
	ds_read_b128 v[184:187], v142 offset:50176
	ds_read_b128 v[188:191], v142 offset:51200
	ds_read_b128 v[192:195], v142 offset:52224
	ds_read_b128 v[212:215], v142 offset:53248
	ds_read_b128 v[216:219], v142 offset:54272
	ds_read_b128 v[220:223], v142 offset:55296
	ds_read_b128 v[232:235], v142 offset:56320
	global_load_lds_dwordx4 v[204:205], off
	s_add_i32 m0, s41, 0x2000
	s_add_u32 s50, s50, 0x40080
	v_lshl_add_u64 v[204:205], v[206:207], 0, s[10:11]
	s_addc_u32 s51, s51, 0
	s_add_i32 s41, s47, s20
	global_load_lds_dwordx4 v[204:205], off
	v_lshl_add_u64 v[204:205], s[50:51], 0, v[196:197]
	s_mov_b32 m0, s41
	s_nop 0
	global_load_lds_dwordx4 v[204:205], off
	v_lshl_add_u64 v[204:205], s[50:51], 0, v[128:129]
	s_add_i32 m0, s41, 0x2000
	s_nop 0
	global_load_lds_dwordx4 v[204:205], off
	v_lshl_add_u64 v[204:205], v[236:237], 0, s[10:11]
	s_mov_b32 m0, s26
	s_nop 0
	global_load_lds_dwordx4 v[204:205], off
	v_lshl_add_u64 v[204:205], v[238:239], 0, s[10:11]
	s_mov_b32 m0, s27
	s_nop 0
	global_load_lds_dwordx4 v[204:205], off
	s_waitcnt vmcnt(8)
	s_waitcnt lgkmcnt(0)
	s_barrier
	s_waitcnt lgkmcnt(0)
	v_mfma_f32_16x16x32_bf16 v[60:63], v[144:147], v[180:183], v[60:63]
	v_mfma_f32_16x16x32_bf16 v[56:59], v[152:155], v[180:183], v[56:59]
	v_mfma_f32_16x16x32_bf16 v[52:55], v[144:147], v[188:191], v[52:55]
	v_mfma_f32_16x16x32_bf16 v[44:47], v[152:155], v[188:191], v[44:47]
	v_mfma_f32_16x16x32_bf16 v[36:39], v[144:147], v[212:215], v[36:39]
	v_mfma_f32_16x16x32_bf16 v[28:31], v[152:155], v[212:215], v[28:31]
	v_mfma_f32_16x16x32_bf16 v[20:23], v[144:147], v[220:223], v[20:23]
	v_mfma_f32_16x16x32_bf16 v[12:15], v[152:155], v[220:223], v[12:15]
	v_mfma_f32_16x16x32_bf16 v[60:63], v[148:151], v[184:187], v[60:63]
	v_mfma_f32_16x16x32_bf16 v[56:59], v[156:159], v[184:187], v[56:59]
	v_mfma_f32_16x16x32_bf16 v[52:55], v[148:151], v[192:195], v[52:55]
	v_mfma_f32_16x16x32_bf16 v[44:47], v[156:159], v[192:195], v[44:47]
	v_mfma_f32_16x16x32_bf16 v[36:39], v[148:151], v[216:219], v[36:39]
	v_mfma_f32_16x16x32_bf16 v[28:31], v[156:159], v[216:219], v[28:31]
	v_mfma_f32_16x16x32_bf16 v[20:23], v[148:151], v[232:235], v[20:23]
	v_mfma_f32_16x16x32_bf16 v[12:15], v[156:159], v[232:235], v[12:15]
	v_mfma_f32_16x16x32_bf16 v[48:51], v[164:167], v[180:183], v[48:51]
	v_mfma_f32_16x16x32_bf16 v[40:43], v[172:175], v[180:183], v[40:43]
	v_mfma_f32_16x16x32_bf16 v[32:35], v[164:167], v[188:191], v[32:35]
	v_mfma_f32_16x16x32_bf16 v[24:27], v[172:175], v[188:191], v[24:27]
	v_mfma_f32_16x16x32_bf16 v[16:19], v[164:167], v[212:215], v[16:19]
	v_mfma_f32_16x16x32_bf16 v[8:11], v[172:175], v[212:215], v[8:11]
	v_mfma_f32_16x16x32_bf16 v[4:7], v[164:167], v[220:223], v[4:7]
	v_mfma_f32_16x16x32_bf16 v[0:3], v[172:175], v[220:223], v[0:3]
	v_mfma_f32_16x16x32_bf16 v[48:51], v[168:171], v[184:187], v[48:51]
	v_mfma_f32_16x16x32_bf16 v[40:43], v[176:179], v[184:187], v[40:43]
	v_mfma_f32_16x16x32_bf16 v[32:35], v[168:171], v[192:195], v[32:35]
	v_mfma_f32_16x16x32_bf16 v[24:27], v[176:179], v[192:195], v[24:27]
	v_mfma_f32_16x16x32_bf16 v[16:19], v[168:171], v[216:219], v[16:19]
	v_mfma_f32_16x16x32_bf16 v[8:11], v[176:179], v[216:219], v[8:11]
	v_mfma_f32_16x16x32_bf16 v[4:7], v[168:171], v[232:235], v[4:7]
	v_mfma_f32_16x16x32_bf16 v[0:3], v[176:179], v[232:235], v[0:3]
	s_add_i32 s37, s37, 2
	s_add_u32 s48, s48, 0x100
	s_addc_u32 s49, s49, 0
	s_add_u32 s35, s35, 0x100
	s_addc_u32 s36, s36, 0
	s_add_u32 s41, s48, 0xfffc0080
	s_addc_u32 s47, s49, -1
	s_add_i32 s54, 0, 0x10000
	s_cmp_eq_u32 s37, 12
	s_cselect_b32 s53, s30, s47
	s_cselect_b32 s52, s31, s41
	v_add_u32_e32 v143, s54, v140
	s_cselect_b32 s51, s19, s36
	s_cselect_b32 s50, s34, s35
	s_add_i32 s41, 0, 0x14000
	s_cmp_gt_u32 s37, 13
	s_barrier
	s_cbranch_scc0 .Lrot_lbb0_98
	s_and_b64 vcc, exec, s[16:17]
	s_cbranch_vccz .LBB0_101
	s_barrier

.Lrot_lbb0_701:
	ds_read_b128 v[148:151], v147
	ds_read_b128 v[152:155], v147 offset:1024
	ds_read_b128 v[156:159], v147 offset:2048
	ds_read_b128 v[164:167], v147 offset:3072
	v_add_u32_e32 v147, s55, v144
	ds_read_b128 v[168:171], v147
	ds_read_b128 v[172:175], v147 offset:1024
	ds_read_b128 v[176:179], v147 offset:2048
	ds_read_b128 v[180:183], v147 offset:3072
	v_lshl_add_u64 v[236:237], v[138:139], 0, s[46:47]
	s_add_i32 m0, s9, 0xc000
	ds_read_b128 v[184:187], v145
	ds_read_b128 v[188:191], v145 offset:1024
	ds_read_b128 v[192:195], v145 offset:2048
	ds_read_b128 v[204:207], v145 offset:3072
	ds_read_b128 v[212:215], v145 offset:4096
	ds_read_b128 v[216:219], v145 offset:5120
	ds_read_b128 v[220:223], v145 offset:6144
	ds_read_b128 v[232:235], v145 offset:7168
	global_load_lds_dwordx4 v[236:237], off
	v_lshl_add_u64 v[236:237], v[140:141], 0, s[46:47]
	s_add_i32 m0, s9, 0xe000
	s_nop 0
	global_load_lds_dwordx4 v[236:237], off
	s_waitcnt vmcnt(8)
	s_waitcnt lgkmcnt(0)
	s_barrier
	s_waitcnt lgkmcnt(0)
	v_mfma_f32_16x16x32_bf16 v[68:71], v[148:151], v[184:187], v[68:71]
	v_mfma_f32_16x16x32_bf16 v[64:67], v[156:159], v[184:187], v[64:67]
	v_mfma_f32_16x16x32_bf16 v[112:115], v[148:151], v[192:195], v[112:115]
	v_mfma_f32_16x16x32_bf16 v[108:111], v[156:159], v[192:195], v[108:111]
	v_mfma_f32_16x16x32_bf16 v[76:79], v[148:151], v[212:215], v[76:79]
	v_mfma_f32_16x16x32_bf16 v[72:75], v[156:159], v[212:215], v[72:75]
	v_mfma_f32_16x16x32_bf16 v[92:95], v[148:151], v[220:223], v[92:95]
	v_mfma_f32_16x16x32_bf16 v[88:91], v[156:159], v[220:223], v[88:91]
	v_mfma_f32_16x16x32_bf16 v[68:71], v[152:155], v[188:191], v[68:71]
	v_mfma_f32_16x16x32_bf16 v[64:67], v[164:167], v[188:191], v[64:67]
	v_mfma_f32_16x16x32_bf16 v[112:115], v[152:155], v[204:207], v[112:115]
	v_mfma_f32_16x16x32_bf16 v[108:111], v[164:167], v[204:207], v[108:111]
	v_mfma_f32_16x16x32_bf16 v[76:79], v[152:155], v[216:219], v[76:79]
	v_mfma_f32_16x16x32_bf16 v[72:75], v[164:167], v[216:219], v[72:75]
	v_mfma_f32_16x16x32_bf16 v[92:95], v[152:155], v[232:235], v[92:95]
	v_mfma_f32_16x16x32_bf16 v[88:91], v[164:167], v[232:235], v[88:91]
	v_mfma_f32_16x16x32_bf16 v[96:99], v[168:171], v[184:187], v[96:99]
	v_mfma_f32_16x16x32_bf16 v[100:103], v[176:179], v[184:187], v[100:103]
	v_mfma_f32_16x16x32_bf16 v[120:123], v[168:171], v[192:195], v[120:123]
	v_mfma_f32_16x16x32_bf16 v[124:127], v[176:179], v[192:195], v[124:127]
	v_mfma_f32_16x16x32_bf16 v[84:87], v[168:171], v[212:215], v[84:87]
	v_mfma_f32_16x16x32_bf16 v[80:83], v[176:179], v[212:215], v[80:83]
	v_mfma_f32_16x16x32_bf16 v[116:119], v[168:171], v[220:223], v[116:119]
	v_mfma_f32_16x16x32_bf16 v[104:107], v[176:179], v[220:223], v[104:107]
	v_mfma_f32_16x16x32_bf16 v[96:99], v[172:175], v[188:191], v[96:99]
	v_mfma_f32_16x16x32_bf16 v[100:103], v[180:183], v[188:191], v[100:103]
	v_mfma_f32_16x16x32_bf16 v[120:123], v[172:175], v[204:207], v[120:123]
	v_mfma_f32_16x16x32_bf16 v[124:127], v[180:183], v[204:207], v[124:127]
	v_mfma_f32_16x16x32_bf16 v[84:87], v[172:175], v[216:219], v[84:87]
	v_mfma_f32_16x16x32_bf16 v[80:83], v[180:183], v[216:219], v[80:83]
	v_mfma_f32_16x16x32_bf16 v[116:119], v[172:175], v[232:235], v[116:119]
	v_mfma_f32_16x16x32_bf16 v[104:107], v[180:183], v[232:235], v[104:107]
	s_barrier
	s_add_i32 s56, s57, s25
	v_lshl_add_u64 v[236:237], s[48:49], 0, v[196:197]
	s_mov_b32 m0, s56
	ds_read_b128 v[184:187], v145 offset:16384
	ds_read_b128 v[188:191], v145 offset:17408
	ds_read_b128 v[192:195], v145 offset:18432
	ds_read_b128 v[204:207], v145 offset:19456
	ds_read_b128 v[212:215], v145 offset:20480
	ds_read_b128 v[216:219], v145 offset:21504
	ds_read_b128 v[220:223], v145 offset:22528
	ds_read_b128 v[232:235], v145 offset:23552
	global_load_lds_dwordx4 v[236:237], off
	s_add_i32 m0, s56, 0x2000
	s_add_u32 s56, s48, 0x40000
	v_lshl_add_u64 v[238:239], s[48:49], 0, v[132:133]
	s_addc_u32 s57, s49, 0
	s_add_i32 s55, s55, s25
	global_load_lds_dwordx4 v[238:239], off
	v_lshl_add_u64 v[240:241], s[56:57], 0, v[196:197]
	s_mov_b32 m0, s55
	v_lshl_add_u64 v[242:243], s[50:51], 0, v[130:131]
	global_load_lds_dwordx4 v[240:241], off
	v_lshl_add_u64 v[240:241], s[56:57], 0, v[132:133]
	s_add_i32 m0, s55, 0x2000
	s_nop 0
	global_load_lds_dwordx4 v[240:241], off
	v_lshl_add_u64 v[240:241], s[50:51], 0, v[128:129]
	s_mov_b32 m0, s9
	s_nop 0
	global_load_lds_dwordx4 v[240:241], off
	s_mov_b32 m0, s27
	s_nop 0
	global_load_lds_dwordx4 v[242:243], off
	s_waitcnt vmcnt(8)
	s_waitcnt lgkmcnt(0)
	s_barrier
	s_waitcnt lgkmcnt(0)
	v_mfma_f32_16x16x32_bf16 v[60:63], v[148:151], v[184:187], v[60:63]
	v_mfma_f32_16x16x32_bf16 v[56:59], v[156:159], v[184:187], v[56:59]
	v_mfma_f32_16x16x32_bf16 v[44:47], v[148:151], v[192:195], v[44:47]
	v_mfma_f32_16x16x32_bf16 v[40:43], v[156:159], v[192:195], v[40:43]
	v_mfma_f32_16x16x32_bf16 v[28:31], v[148:151], v[212:215], v[28:31]
	v_mfma_f32_16x16x32_bf16 v[24:27], v[156:159], v[212:215], v[24:27]
	v_mfma_f32_16x16x32_bf16 v[12:15], v[148:151], v[220:223], v[12:15]
	v_mfma_f32_16x16x32_bf16 v[8:11], v[156:159], v[220:223], v[8:11]
	v_mfma_f32_16x16x32_bf16 v[60:63], v[152:155], v[188:191], v[60:63]
	v_mfma_f32_16x16x32_bf16 v[56:59], v[164:167], v[188:191], v[56:59]
	v_mfma_f32_16x16x32_bf16 v[44:47], v[152:155], v[204:207], v[44:47]
	v_mfma_f32_16x16x32_bf16 v[40:43], v[164:167], v[204:207], v[40:43]
	v_mfma_f32_16x16x32_bf16 v[28:31], v[152:155], v[216:219], v[28:31]
	v_mfma_f32_16x16x32_bf16 v[24:27], v[164:167], v[216:219], v[24:27]
	v_mfma_f32_16x16x32_bf16 v[12:15], v[152:155], v[232:235], v[12:15]
	v_mfma_f32_16x16x32_bf16 v[8:11], v[164:167], v[232:235], v[8:11]
	v_mfma_f32_16x16x32_bf16 v[52:55], v[168:171], v[184:187], v[52:55]
	v_mfma_f32_16x16x32_bf16 v[48:51], v[176:179], v[184:187], v[48:51]
	v_mfma_f32_16x16x32_bf16 v[36:39], v[168:171], v[192:195], v[36:39]
	v_mfma_f32_16x16x32_bf16 v[32:35], v[176:179], v[192:195], v[32:35]
	v_mfma_f32_16x16x32_bf16 v[20:23], v[168:171], v[212:215], v[20:23]
	v_mfma_f32_16x16x32_bf16 v[16:19], v[176:179], v[212:215], v[16:19]
	v_mfma_f32_16x16x32_bf16 v[4:7], v[168:171], v[220:223], v[4:7]
	v_mfma_f32_16x16x32_bf16 v[0:3], v[176:179], v[220:223], v[0:3]
	v_mfma_f32_16x16x32_bf16 v[52:55], v[172:175], v[188:191], v[52:55]
	v_mfma_f32_16x16x32_bf16 v[48:51], v[180:183], v[188:191], v[48:51]
	v_mfma_f32_16x16x32_bf16 v[36:39], v[172:175], v[204:207], v[36:39]
	v_mfma_f32_16x16x32_bf16 v[32:35], v[180:183], v[204:207], v[32:35]
	v_mfma_f32_16x16x32_bf16 v[20:23], v[172:175], v[216:219], v[20:23]
	v_mfma_f32_16x16x32_bf16 v[16:19], v[180:183], v[216:219], v[16:19]
	v_mfma_f32_16x16x32_bf16 v[4:7], v[172:175], v[232:235], v[4:7]
	v_mfma_f32_16x16x32_bf16 v[0:3], v[180:183], v[232:235], v[0:3]
	s_barrier
	s_add_i32 s55, 0, 0x18000
	v_add_u32_e32 v147, s55, v144
	s_add_i32 s56, 0, 0x1c000
	ds_read_b128 v[148:151], v147
	ds_read_b128 v[152:155], v147 offset:1024
	ds_read_b128 v[156:159], v147 offset:2048
	ds_read_b128 v[164:167], v147 offset:3072
	v_add_u32_e32 v147, s56, v144
	ds_read_b128 v[168:171], v147
	ds_read_b128 v[172:175], v147 offset:1024
	ds_read_b128 v[176:179], v147 offset:2048
	ds_read_b128 v[180:183], v147 offset:3072
	s_add_u32 s50, s50, 0x40000
	s_addc_u32 s51, s51, 0
	s_mov_b32 m0, s28
	v_lshl_add_u64 v[244:245], s[50:51], 0, v[128:129]
	ds_read_b128 v[184:187], v145 offset:32768
	ds_read_b128 v[188:191], v145 offset:33792
	ds_read_b128 v[192:195], v145 offset:34816
	ds_read_b128 v[204:207], v145 offset:35840
	ds_read_b128 v[212:215], v145 offset:36864
	ds_read_b128 v[216:219], v145 offset:37888
	ds_read_b128 v[220:223], v145 offset:38912
	ds_read_b128 v[232:235], v145 offset:39936
	global_load_lds_dwordx4 v[244:245], off
	v_lshl_add_u64 v[244:245], s[50:51], 0, v[130:131]
	s_mov_b32 m0, s29
	s_nop 0
	global_load_lds_dwordx4 v[244:245], off
	s_waitcnt vmcnt(8)
	s_waitcnt lgkmcnt(0)
	s_barrier
	s_waitcnt lgkmcnt(0)
	v_mfma_f32_16x16x32_bf16 v[68:71], v[148:151], v[184:187], v[68:71]
	v_mfma_f32_16x16x32_bf16 v[64:67], v[156:159], v[184:187], v[64:67]
	v_mfma_f32_16x16x32_bf16 v[112:115], v[148:151], v[192:195], v[112:115]
	v_mfma_f32_16x16x32_bf16 v[108:111], v[156:159], v[192:195], v[108:111]
	v_mfma_f32_16x16x32_bf16 v[76:79], v[148:151], v[212:215], v[76:79]
	v_mfma_f32_16x16x32_bf16 v[72:75], v[156:159], v[212:215], v[72:75]
	v_mfma_f32_16x16x32_bf16 v[92:95], v[148:151], v[220:223], v[92:95]
	v_mfma_f32_16x16x32_bf16 v[88:91], v[156:159], v[220:223], v[88:91]
	v_mfma_f32_16x16x32_bf16 v[68:71], v[152:155], v[188:191], v[68:71]
	v_mfma_f32_16x16x32_bf16 v[64:67], v[164:167], v[188:191], v[64:67]
	v_mfma_f32_16x16x32_bf16 v[112:115], v[152:155], v[204:207], v[112:115]
	v_mfma_f32_16x16x32_bf16 v[108:111], v[164:167], v[204:207], v[108:111]
	v_mfma_f32_16x16x32_bf16 v[76:79], v[152:155], v[216:219], v[76:79]
	v_mfma_f32_16x16x32_bf16 v[72:75], v[164:167], v[216:219], v[72:75]
	v_mfma_f32_16x16x32_bf16 v[92:95], v[152:155], v[232:235], v[92:95]
	v_mfma_f32_16x16x32_bf16 v[88:91], v[164:167], v[232:235], v[88:91]
	v_mfma_f32_16x16x32_bf16 v[96:99], v[168:171], v[184:187], v[96:99]
	v_mfma_f32_16x16x32_bf16 v[100:103], v[176:179], v[184:187], v[100:103]
	v_mfma_f32_16x16x32_bf16 v[120:123], v[168:171], v[192:195], v[120:123]
	v_mfma_f32_16x16x32_bf16 v[124:127], v[176:179], v[192:195], v[124:127]
	v_mfma_f32_16x16x32_bf16 v[84:87], v[168:171], v[212:215], v[84:87]
	v_mfma_f32_16x16x32_bf16 v[80:83], v[176:179], v[212:215], v[80:83]
	v_mfma_f32_16x16x32_bf16 v[116:119], v[168:171], v[220:223], v[116:119]
	v_mfma_f32_16x16x32_bf16 v[104:107], v[176:179], v[220:223], v[104:107]
	v_mfma_f32_16x16x32_bf16 v[96:99], v[172:175], v[188:191], v[96:99]
	v_mfma_f32_16x16x32_bf16 v[100:103], v[180:183], v[188:191], v[100:103]
	v_mfma_f32_16x16x32_bf16 v[120:123], v[172:175], v[204:207], v[120:123]
	v_mfma_f32_16x16x32_bf16 v[124:127], v[180:183], v[204:207], v[124:127]
	v_mfma_f32_16x16x32_bf16 v[84:87], v[172:175], v[216:219], v[84:87]
	v_mfma_f32_16x16x32_bf16 v[80:83], v[180:183], v[216:219], v[80:83]
	v_mfma_f32_16x16x32_bf16 v[116:119], v[172:175], v[232:235], v[116:119]
	v_mfma_f32_16x16x32_bf16 v[104:107], v[180:183], v[232:235], v[104:107]
	s_barrier
	s_add_i32 s50, s55, s25
	v_lshl_add_u64 v[236:237], v[236:237], 0, s[10:11]
	s_mov_b32 m0, s50
	ds_read_b128 v[184:187], v145 offset:49152
	ds_read_b128 v[188:191], v145 offset:50176
	ds_read_b128 v[192:195], v145 offset:51200
	ds_read_b128 v[204:207], v145 offset:52224
	ds_read_b128 v[212:215], v145 offset:53248
	ds_read_b128 v[216:219], v145 offset:54272
	ds_read_b128 v[220:223], v145 offset:55296
	ds_read_b128 v[232:235], v145 offset:56320
	global_load_lds_dwordx4 v[236:237], off
	s_add_i32 m0, s50, 0x2000
	s_add_u32 s48, s48, 0x40080
	v_lshl_add_u64 v[236:237], v[238:239], 0, s[10:11]
	s_addc_u32 s49, s49, 0
	s_add_i32 s50, s56, s25
	global_load_lds_dwordx4 v[236:237], off
	v_lshl_add_u64 v[236:237], s[48:49], 0, v[196:197]
	s_mov_b32 m0, s50
	s_nop 0
	global_load_lds_dwordx4 v[236:237], off
	v_lshl_add_u64 v[236:237], s[48:49], 0, v[132:133]
	s_add_i32 m0, s50, 0x2000
	s_nop 0
	global_load_lds_dwordx4 v[236:237], off
	v_lshl_add_u64 v[236:237], v[240:241], 0, s[10:11]
	s_mov_b32 m0, s4
	s_nop 0
	global_load_lds_dwordx4 v[236:237], off
	v_lshl_add_u64 v[236:237], v[242:243], 0, s[10:11]
	s_mov_b32 m0, s31
	s_nop 0
	global_load_lds_dwordx4 v[236:237], off
	s_waitcnt vmcnt(8)
	s_waitcnt lgkmcnt(0)
	s_barrier
	s_waitcnt lgkmcnt(0)
	v_mfma_f32_16x16x32_bf16 v[60:63], v[148:151], v[184:187], v[60:63]
	v_mfma_f32_16x16x32_bf16 v[56:59], v[156:159], v[184:187], v[56:59]
	v_mfma_f32_16x16x32_bf16 v[44:47], v[148:151], v[192:195], v[44:47]
	v_mfma_f32_16x16x32_bf16 v[40:43], v[156:159], v[192:195], v[40:43]
	v_mfma_f32_16x16x32_bf16 v[28:31], v[148:151], v[212:215], v[28:31]
	v_mfma_f32_16x16x32_bf16 v[24:27], v[156:159], v[212:215], v[24:27]
	v_mfma_f32_16x16x32_bf16 v[12:15], v[148:151], v[220:223], v[12:15]
	v_mfma_f32_16x16x32_bf16 v[8:11], v[156:159], v[220:223], v[8:11]
	v_mfma_f32_16x16x32_bf16 v[60:63], v[152:155], v[188:191], v[60:63]
	v_mfma_f32_16x16x32_bf16 v[56:59], v[164:167], v[188:191], v[56:59]
	v_mfma_f32_16x16x32_bf16 v[44:47], v[152:155], v[204:207], v[44:47]
	v_mfma_f32_16x16x32_bf16 v[40:43], v[164:167], v[204:207], v[40:43]
	v_mfma_f32_16x16x32_bf16 v[28:31], v[152:155], v[216:219], v[28:31]
	v_mfma_f32_16x16x32_bf16 v[24:27], v[164:167], v[216:219], v[24:27]
	v_mfma_f32_16x16x32_bf16 v[12:15], v[152:155], v[232:235], v[12:15]
	v_mfma_f32_16x16x32_bf16 v[8:11], v[164:167], v[232:235], v[8:11]
	v_mfma_f32_16x16x32_bf16 v[52:55], v[168:171], v[184:187], v[52:55]
	v_mfma_f32_16x16x32_bf16 v[48:51], v[176:179], v[184:187], v[48:51]
	v_mfma_f32_16x16x32_bf16 v[36:39], v[168:171], v[192:195], v[36:39]
	v_mfma_f32_16x16x32_bf16 v[32:35], v[176:179], v[192:195], v[32:35]
	v_mfma_f32_16x16x32_bf16 v[20:23], v[168:171], v[212:215], v[20:23]
	v_mfma_f32_16x16x32_bf16 v[16:19], v[176:179], v[212:215], v[16:19]
	v_mfma_f32_16x16x32_bf16 v[4:7], v[168:171], v[220:223], v[4:7]
	v_mfma_f32_16x16x32_bf16 v[0:3], v[176:179], v[220:223], v[0:3]
	v_mfma_f32_16x16x32_bf16 v[52:55], v[172:175], v[188:191], v[52:55]
	v_mfma_f32_16x16x32_bf16 v[48:51], v[180:183], v[188:191], v[48:51]
	v_mfma_f32_16x16x32_bf16 v[36:39], v[172:175], v[204:207], v[36:39]
	v_mfma_f32_16x16x32_bf16 v[32:35], v[180:183], v[204:207], v[32:35]
	v_mfma_f32_16x16x32_bf16 v[20:23], v[172:175], v[216:219], v[20:23]
	v_mfma_f32_16x16x32_bf16 v[16:19], v[180:183], v[216:219], v[16:19]
	v_mfma_f32_16x16x32_bf16 v[4:7], v[172:175], v[232:235], v[4:7]
	v_mfma_f32_16x16x32_bf16 v[0:3], v[180:183], v[232:235], v[0:3]
	s_add_i32 s54, s54, 2
	s_add_u32 s46, s46, 0x100
	s_addc_u32 s47, s47, 0
	s_add_u32 s48, s14, s46
	s_addc_u32 s49, s15, s47
	s_add_u32 s48, s48, 0x100
	s_addc_u32 s49, s49, 0
	s_add_u32 s55, s36, s46
	s_addc_u32 s56, s37, s47
	s_add_i32 s57, 0, 0x10000
	s_cmpk_eq_i32 s46, 0x700
	s_cselect_b32 s51, s19, s49
	s_cselect_b32 s50, s52, s48
	v_add_u32_e32 v147, s57, v144
	s_cselect_b32 s49, s17, s56
	s_cselect_b32 s48, s53, s55
	s_add_i32 s55, 0, 0x14000
	s_cmp_gt_u32 s54, 13
	s_barrier
	s_cbranch_scc0 .Lrot_lbb0_701
	s_add_u32 s46, s36, 0xffffff00
	s_addc_u32 s47, s37, -1
	s_andn2_b64 vcc, exec, s[40:41]
	s_cbranch_vccnz .LBB0_704
	v_mov_b32_e32 v0, 0
	s_mov_b32 s12, s16
	s_mov_b32 s8, s18
	s_mov_b64 s[14:15], s[44:45]
	s_mov_b32 s34, s35
	v_mov_b32_e32 v1, v0
	v_mov_b32_e32 v2, v0
	v_mov_b32_e32 v3, v0
	v_mov_b32_e32 v4, v0
	v_mov_b32_e32 v5, v0
	v_mov_b32_e32 v6, v0
	v_mov_b32_e32 v7, v0
	v_mov_b32_e32 v16, v0
	v_mov_b32_e32 v17, v0
	v_mov_b32_e32 v18, v0
	v_mov_b32_e32 v19, v0
	v_mov_b32_e32 v20, v0
	v_mov_b32_e32 v21, v0
	v_mov_b32_e32 v22, v0
	v_mov_b32_e32 v23, v0
	v_mov_b32_e32 v32, v0
	v_mov_b32_e32 v33, v0
	v_mov_b32_e32 v34, v0
	v_mov_b32_e32 v35, v0
	v_mov_b32_e32 v36, v0
	v_mov_b32_e32 v37, v0
	v_mov_b32_e32 v38, v0
	v_mov_b32_e32 v39, v0
	v_mov_b32_e32 v48, v0
	v_mov_b32_e32 v49, v0
	v_mov_b32_e32 v50, v0
	v_mov_b32_e32 v51, v0
	v_mov_b32_e32 v52, v0
	v_mov_b32_e32 v53, v0
	v_mov_b32_e32 v54, v0
	v_mov_b32_e32 v55, v0
	v_mov_b32_e32 v8, v0
	v_mov_b32_e32 v9, v0
	v_mov_b32_e32 v10, v0
	v_mov_b32_e32 v11, v0
	v_mov_b32_e32 v12, v0
	v_mov_b32_e32 v13, v0
	v_mov_b32_e32 v14, v0
	v_mov_b32_e32 v15, v0
	v_mov_b32_e32 v24, v0
	v_mov_b32_e32 v25, v0
	v_mov_b32_e32 v26, v0
	v_mov_b32_e32 v27, v0
	v_mov_b32_e32 v28, v0
	v_mov_b32_e32 v29, v0
	v_mov_b32_e32 v30, v0
	v_mov_b32_e32 v31, v0
	v_mov_b32_e32 v40, v0
	v_mov_b32_e32 v41, v0
	v_mov_b32_e32 v42, v0
	v_mov_b32_e32 v43, v0
	v_mov_b32_e32 v44, v0
	v_mov_b32_e32 v45, v0
	v_mov_b32_e32 v46, v0
	v_mov_b32_e32 v47, v0
	v_mov_b32_e32 v56, v0
	v_mov_b32_e32 v57, v0
	v_mov_b32_e32 v58, v0
	v_mov_b32_e32 v59, v0
	v_mov_b32_e32 v60, v0
	v_mov_b32_e32 v61, v0
	v_mov_b32_e32 v62, v0
	v_mov_b32_e32 v63, v0
	v_mov_b32_e32 v104, v0
	v_mov_b32_e32 v105, v0
	v_mov_b32_e32 v106, v0
	v_mov_b32_e32 v107, v0
	v_mov_b32_e32 v116, v0
	v_mov_b32_e32 v117, v0
	v_mov_b32_e32 v118, v0
	v_mov_b32_e32 v119, v0
	v_mov_b32_e32 v80, v0
	v_mov_b32_e32 v81, v0
	v_mov_b32_e32 v82, v0
	v_mov_b32_e32 v83, v0
	v_mov_b32_e32 v84, v0
	v_mov_b32_e32 v85, v0
	v_mov_b32_e32 v86, v0
	v_mov_b32_e32 v87, v0
	v_mov_b32_e32 v124, v0
	v_mov_b32_e32 v125, v0
	v_mov_b32_e32 v126, v0
	v_mov_b32_e32 v127, v0
	v_mov_b32_e32 v120, v0
	v_mov_b32_e32 v121, v0
	v_mov_b32_e32 v122, v0
	v_mov_b32_e32 v123, v0
	v_mov_b32_e32 v100, v0
	v_mov_b32_e32 v101, v0
	v_mov_b32_e32 v102, v0
	v_mov_b32_e32 v103, v0
	v_mov_b32_e32 v96, v0
	v_mov_b32_e32 v97, v0
	v_mov_b32_e32 v98, v0
	v_mov_b32_e32 v99, v0
	v_mov_b32_e32 v88, v0
	v_mov_b32_e32 v89, v0
	v_mov_b32_e32 v90, v0
	v_mov_b32_e32 v91, v0
	v_mov_b32_e32 v92, v0
	v_mov_b32_e32 v93, v0
	v_mov_b32_e32 v94, v0
	v_mov_b32_e32 v95, v0
	v_mov_b32_e32 v72, v0
	v_mov_b32_e32 v73, v0
	v_mov_b32_e32 v74, v0
	v_mov_b32_e32 v75, v0
	v_mov_b32_e32 v76, v0
	v_mov_b32_e32 v77, v0
	v_mov_b32_e32 v78, v0
	v_mov_b32_e32 v79, v0
	v_mov_b32_e32 v108, v0
	v_mov_b32_e32 v109, v0
	v_mov_b32_e32 v110, v0
	v_mov_b32_e32 v111, v0
	v_mov_b32_e32 v112, v0
	v_mov_b32_e32 v113, v0
	v_mov_b32_e32 v114, v0
	v_mov_b32_e32 v115, v0
	v_mov_b32_e32 v64, v0
	v_mov_b32_e32 v65, v0
	v_mov_b32_e32 v66, v0
	v_mov_b32_e32 v67, v0
	v_mov_b32_e32 v68, v0
	v_mov_b32_e32 v69, v0
	v_mov_b32_e32 v70, v0
	v_mov_b32_e32 v71, v0
	s_movk_i32 s52, 0x1fff
	s_mov_b32 s53, 0x7ffff
	s_andn2_b64 vcc, exec, s[38:39]
	s_cbranch_vccnz .LBB0_705
	s_branch .LBB0_706

.Lrot_lbb0_799:
	ds_read_b128 v[142:145], v154
	ds_read_b128 v[146:149], v154 offset:1024
	ds_read_b128 v[150:153], v154 offset:2048
	ds_read_b128 v[154:157], v154 offset:3072
	ds_read_b128 v[164:167], v158
	ds_read_b128 v[168:171], v158 offset:1024
	ds_read_b128 v[172:175], v158 offset:2048
	ds_read_b128 v[176:179], v158 offset:3072
	v_lshl_add_u64 v[158:159], s[46:47], 0, v[134:135]
	s_add_i32 m0, s24, 0xc000
	ds_read_b128 v[180:183], v141
	ds_read_b128 v[184:187], v141 offset:1024
	ds_read_b128 v[188:191], v141 offset:2048
	ds_read_b128 v[192:195], v141 offset:3072
	ds_read_b128 v[204:207], v141 offset:4096
	ds_read_b128 v[212:215], v141 offset:5120
	ds_read_b128 v[216:219], v141 offset:6144
	ds_read_b128 v[220:223], v141 offset:7168
	global_load_lds_dwordx4 v[158:159], off
	v_lshl_add_u64 v[158:159], s[46:47], 0, v[136:137]
	s_add_i32 m0, s24, 0xe000
	s_nop 0
	global_load_lds_dwordx4 v[158:159], off
	s_waitcnt vmcnt(8)
	s_waitcnt lgkmcnt(0)
	s_barrier
	s_waitcnt lgkmcnt(0)
	v_mfma_f32_16x16x32_bf16 v[124:127], v[142:145], v[180:183], v[124:127]
	v_mfma_f32_16x16x32_bf16 v[116:119], v[150:153], v[180:183], v[116:119]
	v_mfma_f32_16x16x32_bf16 v[108:111], v[142:145], v[188:191], v[108:111]
	v_mfma_f32_16x16x32_bf16 v[100:103], v[150:153], v[188:191], v[100:103]
	v_mfma_f32_16x16x32_bf16 v[92:95], v[142:145], v[204:207], v[92:95]
	v_mfma_f32_16x16x32_bf16 v[84:87], v[150:153], v[204:207], v[84:87]
	v_mfma_f32_16x16x32_bf16 v[76:79], v[142:145], v[216:219], v[76:79]
	v_mfma_f32_16x16x32_bf16 v[68:71], v[150:153], v[216:219], v[68:71]
	v_mfma_f32_16x16x32_bf16 v[124:127], v[146:149], v[184:187], v[124:127]
	v_mfma_f32_16x16x32_bf16 v[116:119], v[154:157], v[184:187], v[116:119]
	v_mfma_f32_16x16x32_bf16 v[108:111], v[146:149], v[192:195], v[108:111]
	v_mfma_f32_16x16x32_bf16 v[100:103], v[154:157], v[192:195], v[100:103]
	v_mfma_f32_16x16x32_bf16 v[92:95], v[146:149], v[212:215], v[92:95]
	v_mfma_f32_16x16x32_bf16 v[84:87], v[154:157], v[212:215], v[84:87]
	v_mfma_f32_16x16x32_bf16 v[76:79], v[146:149], v[220:223], v[76:79]
	v_mfma_f32_16x16x32_bf16 v[68:71], v[154:157], v[220:223], v[68:71]
	v_mfma_f32_16x16x32_bf16 v[120:123], v[164:167], v[180:183], v[120:123]
	v_mfma_f32_16x16x32_bf16 v[112:115], v[172:175], v[180:183], v[112:115]
	v_mfma_f32_16x16x32_bf16 v[104:107], v[164:167], v[188:191], v[104:107]
	v_mfma_f32_16x16x32_bf16 v[96:99], v[172:175], v[188:191], v[96:99]
	v_mfma_f32_16x16x32_bf16 v[88:91], v[164:167], v[204:207], v[88:91]
	v_mfma_f32_16x16x32_bf16 v[80:83], v[172:175], v[204:207], v[80:83]
	v_mfma_f32_16x16x32_bf16 v[72:75], v[164:167], v[216:219], v[72:75]
	v_mfma_f32_16x16x32_bf16 v[64:67], v[172:175], v[216:219], v[64:67]
	v_mfma_f32_16x16x32_bf16 v[120:123], v[168:171], v[184:187], v[120:123]
	v_mfma_f32_16x16x32_bf16 v[112:115], v[176:179], v[184:187], v[112:115]
	v_mfma_f32_16x16x32_bf16 v[104:107], v[168:171], v[192:195], v[104:107]
	v_mfma_f32_16x16x32_bf16 v[96:99], v[176:179], v[192:195], v[96:99]
	v_mfma_f32_16x16x32_bf16 v[88:91], v[168:171], v[212:215], v[88:91]
	v_mfma_f32_16x16x32_bf16 v[80:83], v[176:179], v[212:215], v[80:83]
	v_mfma_f32_16x16x32_bf16 v[72:75], v[168:171], v[220:223], v[72:75]
	v_mfma_f32_16x16x32_bf16 v[64:67], v[176:179], v[220:223], v[64:67]
	s_barrier
	s_add_i32 s52, s52, s22
	v_lshl_add_u64 v[158:159], s[48:49], 0, v[196:197]
	s_mov_b32 m0, s52
	ds_read_b128 v[180:183], v141 offset:16384
	ds_read_b128 v[184:187], v141 offset:17408
	ds_read_b128 v[188:191], v141 offset:18432
	ds_read_b128 v[192:195], v141 offset:19456
	ds_read_b128 v[204:207], v141 offset:20480
	ds_read_b128 v[212:215], v141 offset:21504
	ds_read_b128 v[216:219], v141 offset:22528
	ds_read_b128 v[220:223], v141 offset:23552
	global_load_lds_dwordx4 v[158:159], off
	s_add_i32 m0, s52, 0x2000
	s_add_u32 s52, s48, 0x40000
	v_lshl_add_u64 v[232:233], s[48:49], 0, v[128:129]
	s_addc_u32 s53, s49, 0
	s_add_i32 s54, s54, s22
	global_load_lds_dwordx4 v[232:233], off
	v_lshl_add_u64 v[234:235], s[52:53], 0, v[196:197]
	s_mov_b32 m0, s54
	v_lshl_add_u64 v[236:237], s[50:51], 0, v[130:131]
	global_load_lds_dwordx4 v[234:235], off
	v_lshl_add_u64 v[234:235], s[52:53], 0, v[128:129]
	s_add_i32 m0, s54, 0x2000
	s_nop 0
	global_load_lds_dwordx4 v[234:235], off
	v_lshl_add_u64 v[234:235], s[50:51], 0, v[132:133]
	s_mov_b32 m0, s24
	s_nop 0
	global_load_lds_dwordx4 v[234:235], off
	s_mov_b32 m0, s25
	s_nop 0
	global_load_lds_dwordx4 v[236:237], off
	s_waitcnt vmcnt(8)
	s_waitcnt lgkmcnt(0)
	s_barrier
	s_waitcnt lgkmcnt(0)
	v_mfma_f32_16x16x32_bf16 v[60:63], v[142:145], v[180:183], v[60:63]
	v_mfma_f32_16x16x32_bf16 v[52:55], v[150:153], v[180:183], v[52:55]
	v_mfma_f32_16x16x32_bf16 v[44:47], v[142:145], v[188:191], v[44:47]
	v_mfma_f32_16x16x32_bf16 v[36:39], v[150:153], v[188:191], v[36:39]
	v_mfma_f32_16x16x32_bf16 v[28:31], v[142:145], v[204:207], v[28:31]
	v_mfma_f32_16x16x32_bf16 v[20:23], v[150:153], v[204:207], v[20:23]
	v_mfma_f32_16x16x32_bf16 v[12:15], v[142:145], v[216:219], v[12:15]
	v_mfma_f32_16x16x32_bf16 v[4:7], v[150:153], v[216:219], v[4:7]
	v_mfma_f32_16x16x32_bf16 v[60:63], v[146:149], v[184:187], v[60:63]
	v_mfma_f32_16x16x32_bf16 v[52:55], v[154:157], v[184:187], v[52:55]
	v_mfma_f32_16x16x32_bf16 v[44:47], v[146:149], v[192:195], v[44:47]
	v_mfma_f32_16x16x32_bf16 v[36:39], v[154:157], v[192:195], v[36:39]
	v_mfma_f32_16x16x32_bf16 v[28:31], v[146:149], v[212:215], v[28:31]
	v_mfma_f32_16x16x32_bf16 v[20:23], v[154:157], v[212:215], v[20:23]
	v_mfma_f32_16x16x32_bf16 v[12:15], v[146:149], v[220:223], v[12:15]
	v_mfma_f32_16x16x32_bf16 v[4:7], v[154:157], v[220:223], v[4:7]
	v_mfma_f32_16x16x32_bf16 v[56:59], v[164:167], v[180:183], v[56:59]
	v_mfma_f32_16x16x32_bf16 v[48:51], v[172:175], v[180:183], v[48:51]
	v_mfma_f32_16x16x32_bf16 v[40:43], v[164:167], v[188:191], v[40:43]
	v_mfma_f32_16x16x32_bf16 v[32:35], v[172:175], v[188:191], v[32:35]
	v_mfma_f32_16x16x32_bf16 v[24:27], v[164:167], v[204:207], v[24:27]
	v_mfma_f32_16x16x32_bf16 v[16:19], v[172:175], v[204:207], v[16:19]
	v_mfma_f32_16x16x32_bf16 v[8:11], v[164:167], v[216:219], v[8:11]
	v_mfma_f32_16x16x32_bf16 v[0:3], v[172:175], v[216:219], v[0:3]
	v_mfma_f32_16x16x32_bf16 v[56:59], v[168:171], v[184:187], v[56:59]
	v_mfma_f32_16x16x32_bf16 v[48:51], v[176:179], v[184:187], v[48:51]
	v_mfma_f32_16x16x32_bf16 v[40:43], v[168:171], v[192:195], v[40:43]
	v_mfma_f32_16x16x32_bf16 v[32:35], v[176:179], v[192:195], v[32:35]
	v_mfma_f32_16x16x32_bf16 v[24:27], v[168:171], v[212:215], v[24:27]
	v_mfma_f32_16x16x32_bf16 v[16:19], v[176:179], v[212:215], v[16:19]
	v_mfma_f32_16x16x32_bf16 v[8:11], v[168:171], v[220:223], v[8:11]
	v_mfma_f32_16x16x32_bf16 v[0:3], v[176:179], v[220:223], v[0:3]
	s_barrier
	s_add_i32 s52, 0, 0x18000
	s_add_i32 s53, 0, 0x1c000
	v_add_u32_e32 v154, s52, v139
	v_add_u32_e32 v176, s53, v139
	ds_read_b128 v[142:145], v154
	ds_read_b128 v[146:149], v154 offset:1024
	ds_read_b128 v[150:153], v154 offset:2048
	ds_read_b128 v[154:157], v154 offset:3072
	ds_read_b128 v[164:167], v176
	ds_read_b128 v[168:171], v176 offset:1024
	ds_read_b128 v[172:175], v176 offset:2048
	ds_read_b128 v[176:179], v176 offset:3072
	s_add_u32 s50, s50, 0x40000
	s_addc_u32 s51, s51, 0
	s_mov_b32 m0, s26
	v_lshl_add_u64 v[238:239], s[50:51], 0, v[132:133]
	ds_read_b128 v[180:183], v141 offset:32768
	ds_read_b128 v[184:187], v141 offset:33792
	ds_read_b128 v[188:191], v141 offset:34816
	ds_read_b128 v[192:195], v141 offset:35840
	ds_read_b128 v[204:207], v141 offset:36864
	ds_read_b128 v[212:215], v141 offset:37888
	ds_read_b128 v[216:219], v141 offset:38912
	ds_read_b128 v[220:223], v141 offset:39936
	global_load_lds_dwordx4 v[238:239], off
	v_lshl_add_u64 v[238:239], s[50:51], 0, v[130:131]
	s_mov_b32 m0, s27
	s_nop 0
	global_load_lds_dwordx4 v[238:239], off
	s_waitcnt vmcnt(8)
	s_waitcnt lgkmcnt(0)
	s_barrier
	s_waitcnt lgkmcnt(0)
	v_mfma_f32_16x16x32_bf16 v[124:127], v[142:145], v[180:183], v[124:127]
	v_mfma_f32_16x16x32_bf16 v[116:119], v[150:153], v[180:183], v[116:119]
	v_mfma_f32_16x16x32_bf16 v[108:111], v[142:145], v[188:191], v[108:111]
	v_mfma_f32_16x16x32_bf16 v[100:103], v[150:153], v[188:191], v[100:103]
	v_mfma_f32_16x16x32_bf16 v[92:95], v[142:145], v[204:207], v[92:95]
	v_mfma_f32_16x16x32_bf16 v[84:87], v[150:153], v[204:207], v[84:87]
	v_mfma_f32_16x16x32_bf16 v[76:79], v[142:145], v[216:219], v[76:79]
	v_mfma_f32_16x16x32_bf16 v[68:71], v[150:153], v[216:219], v[68:71]
	v_mfma_f32_16x16x32_bf16 v[124:127], v[146:149], v[184:187], v[124:127]
	v_mfma_f32_16x16x32_bf16 v[116:119], v[154:157], v[184:187], v[116:119]
	v_mfma_f32_16x16x32_bf16 v[108:111], v[146:149], v[192:195], v[108:111]
	v_mfma_f32_16x16x32_bf16 v[100:103], v[154:157], v[192:195], v[100:103]
	v_mfma_f32_16x16x32_bf16 v[92:95], v[146:149], v[212:215], v[92:95]
	v_mfma_f32_16x16x32_bf16 v[84:87], v[154:157], v[212:215], v[84:87]
	v_mfma_f32_16x16x32_bf16 v[76:79], v[146:149], v[220:223], v[76:79]
	v_mfma_f32_16x16x32_bf16 v[68:71], v[154:157], v[220:223], v[68:71]
	v_mfma_f32_16x16x32_bf16 v[120:123], v[164:167], v[180:183], v[120:123]
	v_mfma_f32_16x16x32_bf16 v[112:115], v[172:175], v[180:183], v[112:115]
	v_mfma_f32_16x16x32_bf16 v[104:107], v[164:167], v[188:191], v[104:107]
	v_mfma_f32_16x16x32_bf16 v[96:99], v[172:175], v[188:191], v[96:99]
	v_mfma_f32_16x16x32_bf16 v[88:91], v[164:167], v[204:207], v[88:91]
	v_mfma_f32_16x16x32_bf16 v[80:83], v[172:175], v[204:207], v[80:83]
	v_mfma_f32_16x16x32_bf16 v[72:75], v[164:167], v[216:219], v[72:75]
	v_mfma_f32_16x16x32_bf16 v[64:67], v[172:175], v[216:219], v[64:67]
	v_mfma_f32_16x16x32_bf16 v[120:123], v[168:171], v[184:187], v[120:123]
	v_mfma_f32_16x16x32_bf16 v[112:115], v[176:179], v[184:187], v[112:115]
	v_mfma_f32_16x16x32_bf16 v[104:107], v[168:171], v[192:195], v[104:107]
	v_mfma_f32_16x16x32_bf16 v[96:99], v[176:179], v[192:195], v[96:99]
	v_mfma_f32_16x16x32_bf16 v[88:91], v[168:171], v[212:215], v[88:91]
	v_mfma_f32_16x16x32_bf16 v[80:83], v[176:179], v[212:215], v[80:83]
	v_mfma_f32_16x16x32_bf16 v[72:75], v[168:171], v[220:223], v[72:75]
	v_mfma_f32_16x16x32_bf16 v[64:67], v[176:179], v[220:223], v[64:67]
	s_barrier
	s_add_i32 s50, s52, s22
	v_lshl_add_u64 v[158:159], v[158:159], 0, s[10:11]
	s_mov_b32 m0, s50
	ds_read_b128 v[180:183], v141 offset:49152
	ds_read_b128 v[184:187], v141 offset:50176
	ds_read_b128 v[188:191], v141 offset:51200
	ds_read_b128 v[192:195], v141 offset:52224
	ds_read_b128 v[204:207], v141 offset:53248
	ds_read_b128 v[212:215], v141 offset:54272
	ds_read_b128 v[216:219], v141 offset:55296
	ds_read_b128 v[220:223], v141 offset:56320
	global_load_lds_dwordx4 v[158:159], off
	s_add_i32 m0, s50, 0x2000
	s_add_u32 s48, s48, 0x40080
	v_lshl_add_u64 v[158:159], v[232:233], 0, s[10:11]
	s_addc_u32 s49, s49, 0
	s_add_i32 s50, s53, s22
	global_load_lds_dwordx4 v[158:159], off
	v_lshl_add_u64 v[158:159], s[48:49], 0, v[196:197]
	s_mov_b32 m0, s50
	s_nop 0
	global_load_lds_dwordx4 v[158:159], off
	v_lshl_add_u64 v[158:159], s[48:49], 0, v[128:129]
	s_add_i32 m0, s50, 0x2000
	s_nop 0
	global_load_lds_dwordx4 v[158:159], off
	v_lshl_add_u64 v[158:159], v[234:235], 0, s[10:11]
	s_mov_b32 m0, s4
	s_nop 0
	global_load_lds_dwordx4 v[158:159], off
	v_lshl_add_u64 v[158:159], v[236:237], 0, s[10:11]
	s_mov_b32 m0, s28
	s_nop 0
	global_load_lds_dwordx4 v[158:159], off
	s_waitcnt vmcnt(8)
	s_waitcnt lgkmcnt(0)
	s_barrier
	s_waitcnt lgkmcnt(0)
	v_mfma_f32_16x16x32_bf16 v[60:63], v[142:145], v[180:183], v[60:63]
	v_mfma_f32_16x16x32_bf16 v[52:55], v[150:153], v[180:183], v[52:55]
	v_mfma_f32_16x16x32_bf16 v[44:47], v[142:145], v[188:191], v[44:47]
	v_mfma_f32_16x16x32_bf16 v[36:39], v[150:153], v[188:191], v[36:39]
	v_mfma_f32_16x16x32_bf16 v[28:31], v[142:145], v[204:207], v[28:31]
	v_mfma_f32_16x16x32_bf16 v[20:23], v[150:153], v[204:207], v[20:23]
	v_mfma_f32_16x16x32_bf16 v[12:15], v[142:145], v[216:219], v[12:15]
	v_mfma_f32_16x16x32_bf16 v[4:7], v[150:153], v[216:219], v[4:7]
	v_mfma_f32_16x16x32_bf16 v[60:63], v[146:149], v[184:187], v[60:63]
	v_mfma_f32_16x16x32_bf16 v[52:55], v[154:157], v[184:187], v[52:55]
	v_mfma_f32_16x16x32_bf16 v[44:47], v[146:149], v[192:195], v[44:47]
	v_mfma_f32_16x16x32_bf16 v[36:39], v[154:157], v[192:195], v[36:39]
	v_mfma_f32_16x16x32_bf16 v[28:31], v[146:149], v[212:215], v[28:31]
	v_mfma_f32_16x16x32_bf16 v[20:23], v[154:157], v[212:215], v[20:23]
	v_mfma_f32_16x16x32_bf16 v[12:15], v[146:149], v[220:223], v[12:15]
	v_mfma_f32_16x16x32_bf16 v[4:7], v[154:157], v[220:223], v[4:7]
	v_mfma_f32_16x16x32_bf16 v[56:59], v[164:167], v[180:183], v[56:59]
	v_mfma_f32_16x16x32_bf16 v[48:51], v[172:175], v[180:183], v[48:51]
	v_mfma_f32_16x16x32_bf16 v[40:43], v[164:167], v[188:191], v[40:43]
	v_mfma_f32_16x16x32_bf16 v[32:35], v[172:175], v[188:191], v[32:35]
	v_mfma_f32_16x16x32_bf16 v[24:27], v[164:167], v[204:207], v[24:27]
	v_mfma_f32_16x16x32_bf16 v[16:19], v[172:175], v[204:207], v[16:19]
	v_mfma_f32_16x16x32_bf16 v[8:11], v[164:167], v[216:219], v[8:11]
	v_mfma_f32_16x16x32_bf16 v[0:3], v[172:175], v[216:219], v[0:3]
	v_mfma_f32_16x16x32_bf16 v[56:59], v[168:171], v[184:187], v[56:59]
	v_mfma_f32_16x16x32_bf16 v[48:51], v[176:179], v[184:187], v[48:51]
	v_mfma_f32_16x16x32_bf16 v[40:43], v[168:171], v[192:195], v[40:43]
	v_mfma_f32_16x16x32_bf16 v[32:35], v[176:179], v[192:195], v[32:35]
	v_mfma_f32_16x16x32_bf16 v[24:27], v[168:171], v[212:215], v[24:27]
	v_mfma_f32_16x16x32_bf16 v[16:19], v[176:179], v[212:215], v[16:19]
	v_mfma_f32_16x16x32_bf16 v[8:11], v[168:171], v[220:223], v[8:11]
	v_mfma_f32_16x16x32_bf16 v[0:3], v[176:179], v[220:223], v[0:3]
	s_add_i32 s45, s45, 2
	s_add_u32 s46, s46, 0x100
	s_addc_u32 s47, s47, 0
	s_add_u32 s36, s36, 0x100
	s_addc_u32 s37, s37, 0
	s_add_u32 s48, s46, 0xfffc0080
	s_addc_u32 s49, s47, -1
	s_add_i32 s52, 0, 0x10000
	s_cmp_eq_u32 s45, 12
	s_cselect_b32 s51, s19, s49
	s_cselect_b32 s50, s34, s48
	s_cselect_b32 s49, s17, s37
	s_cselect_b32 s48, s35, s36
	s_add_i32 s54, 0, 0x14000
	v_add_u32_e32 v154, s52, v139
	v_add_u32_e32 v158, s54, v139
	s_cmp_gt_u32 s45, 13
	s_barrier
	s_cbranch_scc0 .Lrot_lbb0_799
	s_and_b64 vcc, exec, s[14:15]
	s_cbranch_vccz .LBB0_802
	s_barrier

.Lrot_lbb0_903:
	ds_read_b128 v[138:141], v154
	ds_read_b128 v[146:149], v154 offset:1024
	ds_read_b128 v[150:153], v154 offset:2048
	ds_read_b128 v[154:157], v154 offset:3072
	ds_read_b128 v[164:167], v158
	ds_read_b128 v[168:171], v158 offset:1024
	ds_read_b128 v[172:175], v158 offset:2048
	ds_read_b128 v[176:179], v158 offset:3072
	v_lshl_add_u64 v[158:159], s[18:19], 0, v[134:135]
	s_add_i32 m0, s23, 0xc000
	ds_read_b128 v[180:183], v145
	ds_read_b128 v[184:187], v145 offset:1024
	ds_read_b128 v[188:191], v145 offset:2048
	ds_read_b128 v[192:195], v145 offset:3072
	ds_read_b128 v[204:207], v145 offset:4096
	ds_read_b128 v[212:215], v145 offset:5120
	ds_read_b128 v[216:219], v145 offset:6144
	ds_read_b128 v[220:223], v145 offset:7168
	global_load_lds_dwordx4 v[158:159], off
	v_lshl_add_u64 v[158:159], s[18:19], 0, v[136:137]
	s_add_i32 m0, s23, 0xe000
	s_nop 0
	global_load_lds_dwordx4 v[158:159], off
	s_waitcnt vmcnt(8)
	s_waitcnt lgkmcnt(0)
	s_barrier
	s_waitcnt lgkmcnt(0)
	v_mfma_f32_16x16x32_bf16 v[124:127], v[138:141], v[180:183], v[124:127]
	v_mfma_f32_16x16x32_bf16 v[120:123], v[150:153], v[180:183], v[120:123]
	v_mfma_f32_16x16x32_bf16 v[112:115], v[138:141], v[188:191], v[112:115]
	v_mfma_f32_16x16x32_bf16 v[104:107], v[150:153], v[188:191], v[104:107]
	v_mfma_f32_16x16x32_bf16 v[96:99], v[138:141], v[204:207], v[96:99]
	v_mfma_f32_16x16x32_bf16 v[88:91], v[150:153], v[204:207], v[88:91]
	v_mfma_f32_16x16x32_bf16 v[80:83], v[138:141], v[216:219], v[80:83]
	v_mfma_f32_16x16x32_bf16 v[72:75], v[150:153], v[216:219], v[72:75]
	v_mfma_f32_16x16x32_bf16 v[124:127], v[146:149], v[184:187], v[124:127]
	v_mfma_f32_16x16x32_bf16 v[120:123], v[154:157], v[184:187], v[120:123]
	v_mfma_f32_16x16x32_bf16 v[112:115], v[146:149], v[192:195], v[112:115]
	v_mfma_f32_16x16x32_bf16 v[104:107], v[154:157], v[192:195], v[104:107]
	v_mfma_f32_16x16x32_bf16 v[96:99], v[146:149], v[212:215], v[96:99]
	v_mfma_f32_16x16x32_bf16 v[88:91], v[154:157], v[212:215], v[88:91]
	v_mfma_f32_16x16x32_bf16 v[80:83], v[146:149], v[220:223], v[80:83]
	v_mfma_f32_16x16x32_bf16 v[72:75], v[154:157], v[220:223], v[72:75]
	v_mfma_f32_16x16x32_bf16 v[116:119], v[164:167], v[180:183], v[116:119]
	v_mfma_f32_16x16x32_bf16 v[108:111], v[172:175], v[180:183], v[108:111]
	v_mfma_f32_16x16x32_bf16 v[100:103], v[164:167], v[188:191], v[100:103]
	v_mfma_f32_16x16x32_bf16 v[92:95], v[172:175], v[188:191], v[92:95]
	v_mfma_f32_16x16x32_bf16 v[84:87], v[164:167], v[204:207], v[84:87]
	v_mfma_f32_16x16x32_bf16 v[76:79], v[172:175], v[204:207], v[76:79]
	v_mfma_f32_16x16x32_bf16 v[68:71], v[164:167], v[216:219], v[68:71]
	v_mfma_f32_16x16x32_bf16 v[64:67], v[172:175], v[216:219], v[64:67]
	v_mfma_f32_16x16x32_bf16 v[116:119], v[168:171], v[184:187], v[116:119]
	v_mfma_f32_16x16x32_bf16 v[108:111], v[176:179], v[184:187], v[108:111]
	v_mfma_f32_16x16x32_bf16 v[100:103], v[168:171], v[192:195], v[100:103]
	v_mfma_f32_16x16x32_bf16 v[92:95], v[176:179], v[192:195], v[92:95]
	v_mfma_f32_16x16x32_bf16 v[84:87], v[168:171], v[212:215], v[84:87]
	v_mfma_f32_16x16x32_bf16 v[76:79], v[176:179], v[212:215], v[76:79]
	v_mfma_f32_16x16x32_bf16 v[68:71], v[168:171], v[220:223], v[68:71]
	v_mfma_f32_16x16x32_bf16 v[64:67], v[176:179], v[220:223], v[64:67]
	s_barrier
	s_add_i32 s18, s48, s22
	v_lshl_add_u64 v[158:159], s[42:43], 0, v[196:197]
	s_mov_b32 m0, s18
	ds_read_b128 v[180:183], v145 offset:16384
	ds_read_b128 v[184:187], v145 offset:17408
	ds_read_b128 v[188:191], v145 offset:18432
	ds_read_b128 v[192:195], v145 offset:19456
	ds_read_b128 v[204:207], v145 offset:20480
	ds_read_b128 v[212:215], v145 offset:21504
	ds_read_b128 v[216:219], v145 offset:22528
	ds_read_b128 v[220:223], v145 offset:23552
	global_load_lds_dwordx4 v[158:159], off
	s_add_i32 m0, s18, 0x2000
	s_add_u32 s18, s42, 0xb0000
	v_lshl_add_u64 v[232:233], s[42:43], 0, v[132:133]
	s_addc_u32 s19, s43, 0
	s_add_i32 s48, s49, s22
	global_load_lds_dwordx4 v[232:233], off
	v_lshl_add_u64 v[234:235], s[18:19], 0, v[196:197]
	s_mov_b32 m0, s48
	v_lshl_add_u64 v[236:237], s[44:45], 0, v[130:131]
	global_load_lds_dwordx4 v[234:235], off
	v_lshl_add_u64 v[234:235], s[18:19], 0, v[132:133]
	s_add_i32 m0, s48, 0x2000
	s_nop 0
	global_load_lds_dwordx4 v[234:235], off
	v_lshl_add_u64 v[234:235], s[44:45], 0, v[128:129]
	s_mov_b32 m0, s23
	s_nop 0
	global_load_lds_dwordx4 v[234:235], off
	s_mov_b32 m0, s24
	s_nop 0
	global_load_lds_dwordx4 v[236:237], off
	s_waitcnt vmcnt(8)
	s_waitcnt lgkmcnt(0)
	s_barrier
	s_waitcnt lgkmcnt(0)
	v_mfma_f32_16x16x32_bf16 v[60:63], v[138:141], v[180:183], v[60:63]
	v_mfma_f32_16x16x32_bf16 v[56:59], v[150:153], v[180:183], v[56:59]
	v_mfma_f32_16x16x32_bf16 v[48:51], v[138:141], v[188:191], v[48:51]
	v_mfma_f32_16x16x32_bf16 v[40:43], v[150:153], v[188:191], v[40:43]
	v_mfma_f32_16x16x32_bf16 v[32:35], v[138:141], v[204:207], v[32:35]
	v_mfma_f32_16x16x32_bf16 v[24:27], v[150:153], v[204:207], v[24:27]
	v_mfma_f32_16x16x32_bf16 v[16:19], v[138:141], v[216:219], v[16:19]
	v_mfma_f32_16x16x32_bf16 v[8:11], v[150:153], v[216:219], v[8:11]
	v_mfma_f32_16x16x32_bf16 v[60:63], v[146:149], v[184:187], v[60:63]
	v_mfma_f32_16x16x32_bf16 v[56:59], v[154:157], v[184:187], v[56:59]
	v_mfma_f32_16x16x32_bf16 v[48:51], v[146:149], v[192:195], v[48:51]
	v_mfma_f32_16x16x32_bf16 v[40:43], v[154:157], v[192:195], v[40:43]
	v_mfma_f32_16x16x32_bf16 v[32:35], v[146:149], v[212:215], v[32:35]
	v_mfma_f32_16x16x32_bf16 v[24:27], v[154:157], v[212:215], v[24:27]
	v_mfma_f32_16x16x32_bf16 v[16:19], v[146:149], v[220:223], v[16:19]
	v_mfma_f32_16x16x32_bf16 v[8:11], v[154:157], v[220:223], v[8:11]
	v_mfma_f32_16x16x32_bf16 v[52:55], v[164:167], v[180:183], v[52:55]
	v_mfma_f32_16x16x32_bf16 v[44:47], v[172:175], v[180:183], v[44:47]
	v_mfma_f32_16x16x32_bf16 v[36:39], v[164:167], v[188:191], v[36:39]
	v_mfma_f32_16x16x32_bf16 v[28:31], v[172:175], v[188:191], v[28:31]
	v_mfma_f32_16x16x32_bf16 v[20:23], v[164:167], v[204:207], v[20:23]
	v_mfma_f32_16x16x32_bf16 v[12:15], v[172:175], v[204:207], v[12:15]
	v_mfma_f32_16x16x32_bf16 v[4:7], v[164:167], v[216:219], v[4:7]
	v_mfma_f32_16x16x32_bf16 v[0:3], v[172:175], v[216:219], v[0:3]
	v_mfma_f32_16x16x32_bf16 v[52:55], v[168:171], v[184:187], v[52:55]
	v_mfma_f32_16x16x32_bf16 v[44:47], v[176:179], v[184:187], v[44:47]
	v_mfma_f32_16x16x32_bf16 v[36:39], v[168:171], v[192:195], v[36:39]
	v_mfma_f32_16x16x32_bf16 v[28:31], v[176:179], v[192:195], v[28:31]
	v_mfma_f32_16x16x32_bf16 v[20:23], v[168:171], v[212:215], v[20:23]
	v_mfma_f32_16x16x32_bf16 v[12:15], v[176:179], v[212:215], v[12:15]
	v_mfma_f32_16x16x32_bf16 v[4:7], v[168:171], v[220:223], v[4:7]
	v_mfma_f32_16x16x32_bf16 v[0:3], v[176:179], v[220:223], v[0:3]
	s_barrier
	s_add_i32 s48, 0, 0x18000
	s_add_i32 s49, 0, 0x1c000
	v_add_u32_e32 v154, s48, v143
	v_add_u32_e32 v176, s49, v143
	ds_read_b128 v[138:141], v154
	ds_read_b128 v[146:149], v154 offset:1024
	ds_read_b128 v[150:153], v154 offset:2048
	ds_read_b128 v[154:157], v154 offset:3072
	ds_read_b128 v[164:167], v176
	ds_read_b128 v[168:171], v176 offset:1024
	ds_read_b128 v[172:175], v176 offset:2048
	ds_read_b128 v[176:179], v176 offset:3072
	s_add_u32 s18, s44, 0xb0000
	s_addc_u32 s19, s45, 0
	s_mov_b32 m0, s25
	v_lshl_add_u64 v[238:239], s[18:19], 0, v[128:129]
	ds_read_b128 v[180:183], v145 offset:32768
	ds_read_b128 v[184:187], v145 offset:33792
	ds_read_b128 v[188:191], v145 offset:34816
	ds_read_b128 v[192:195], v145 offset:35840
	ds_read_b128 v[204:207], v145 offset:36864
	ds_read_b128 v[212:215], v145 offset:37888
	ds_read_b128 v[216:219], v145 offset:38912
	ds_read_b128 v[220:223], v145 offset:39936
	global_load_lds_dwordx4 v[238:239], off
	v_lshl_add_u64 v[238:239], s[18:19], 0, v[130:131]
	s_mov_b32 m0, s26
	s_nop 0
	global_load_lds_dwordx4 v[238:239], off
	s_waitcnt vmcnt(8)
	s_waitcnt lgkmcnt(0)
	s_barrier
	s_waitcnt lgkmcnt(0)
	v_mfma_f32_16x16x32_bf16 v[124:127], v[138:141], v[180:183], v[124:127]
	v_mfma_f32_16x16x32_bf16 v[120:123], v[150:153], v[180:183], v[120:123]
	v_mfma_f32_16x16x32_bf16 v[112:115], v[138:141], v[188:191], v[112:115]
	v_mfma_f32_16x16x32_bf16 v[104:107], v[150:153], v[188:191], v[104:107]
	v_mfma_f32_16x16x32_bf16 v[96:99], v[138:141], v[204:207], v[96:99]
	v_mfma_f32_16x16x32_bf16 v[88:91], v[150:153], v[204:207], v[88:91]
	v_mfma_f32_16x16x32_bf16 v[80:83], v[138:141], v[216:219], v[80:83]
	v_mfma_f32_16x16x32_bf16 v[72:75], v[150:153], v[216:219], v[72:75]
	v_mfma_f32_16x16x32_bf16 v[124:127], v[146:149], v[184:187], v[124:127]
	v_mfma_f32_16x16x32_bf16 v[120:123], v[154:157], v[184:187], v[120:123]
	v_mfma_f32_16x16x32_bf16 v[112:115], v[146:149], v[192:195], v[112:115]
	v_mfma_f32_16x16x32_bf16 v[104:107], v[154:157], v[192:195], v[104:107]
	v_mfma_f32_16x16x32_bf16 v[96:99], v[146:149], v[212:215], v[96:99]
	v_mfma_f32_16x16x32_bf16 v[88:91], v[154:157], v[212:215], v[88:91]
	v_mfma_f32_16x16x32_bf16 v[80:83], v[146:149], v[220:223], v[80:83]
	v_mfma_f32_16x16x32_bf16 v[72:75], v[154:157], v[220:223], v[72:75]
	v_mfma_f32_16x16x32_bf16 v[116:119], v[164:167], v[180:183], v[116:119]
	v_mfma_f32_16x16x32_bf16 v[108:111], v[172:175], v[180:183], v[108:111]
	v_mfma_f32_16x16x32_bf16 v[100:103], v[164:167], v[188:191], v[100:103]
	v_mfma_f32_16x16x32_bf16 v[92:95], v[172:175], v[188:191], v[92:95]
	v_mfma_f32_16x16x32_bf16 v[84:87], v[164:167], v[204:207], v[84:87]
	v_mfma_f32_16x16x32_bf16 v[76:79], v[172:175], v[204:207], v[76:79]
	v_mfma_f32_16x16x32_bf16 v[68:71], v[164:167], v[216:219], v[68:71]
	v_mfma_f32_16x16x32_bf16 v[64:67], v[172:175], v[216:219], v[64:67]
	v_mfma_f32_16x16x32_bf16 v[116:119], v[168:171], v[184:187], v[116:119]
	v_mfma_f32_16x16x32_bf16 v[108:111], v[176:179], v[184:187], v[108:111]
	v_mfma_f32_16x16x32_bf16 v[100:103], v[168:171], v[192:195], v[100:103]
	v_mfma_f32_16x16x32_bf16 v[92:95], v[176:179], v[192:195], v[92:95]
	v_mfma_f32_16x16x32_bf16 v[84:87], v[168:171], v[212:215], v[84:87]
	v_mfma_f32_16x16x32_bf16 v[76:79], v[176:179], v[212:215], v[76:79]
	v_mfma_f32_16x16x32_bf16 v[68:71], v[168:171], v[220:223], v[68:71]
	v_mfma_f32_16x16x32_bf16 v[64:67], v[176:179], v[220:223], v[64:67]
	s_barrier
	s_add_i32 s18, s48, s22
	v_lshl_add_u64 v[158:159], v[158:159], 0, s[10:11]
	s_mov_b32 m0, s18
	ds_read_b128 v[180:183], v145 offset:49152
	ds_read_b128 v[184:187], v145 offset:50176
	ds_read_b128 v[188:191], v145 offset:51200
	ds_read_b128 v[192:195], v145 offset:52224
	ds_read_b128 v[204:207], v145 offset:53248
	ds_read_b128 v[212:215], v145 offset:54272
	ds_read_b128 v[216:219], v145 offset:55296
	ds_read_b128 v[220:223], v145 offset:56320
	global_load_lds_dwordx4 v[158:159], off
	s_add_i32 m0, s18, 0x2000
	s_add_u32 s18, s42, 0xb0080
	v_lshl_add_u64 v[158:159], v[232:233], 0, s[10:11]
	s_addc_u32 s19, s43, 0
	s_add_i32 s42, s49, s22
	global_load_lds_dwordx4 v[158:159], off
	v_lshl_add_u64 v[158:159], s[18:19], 0, v[196:197]
	s_mov_b32 m0, s42
	s_nop 0
	global_load_lds_dwordx4 v[158:159], off
	v_lshl_add_u64 v[158:159], s[18:19], 0, v[132:133]
	s_add_i32 m0, s42, 0x2000
	s_nop 0
	global_load_lds_dwordx4 v[158:159], off
	v_lshl_add_u64 v[158:159], v[234:235], 0, s[10:11]
	s_mov_b32 m0, s27
	s_nop 0
	global_load_lds_dwordx4 v[158:159], off
	v_lshl_add_u64 v[158:159], v[236:237], 0, s[10:11]
	s_mov_b32 m0, s28
	s_nop 0
	global_load_lds_dwordx4 v[158:159], off
	s_waitcnt vmcnt(8)
	s_waitcnt lgkmcnt(0)
	s_barrier
	s_waitcnt lgkmcnt(0)
	v_mfma_f32_16x16x32_bf16 v[60:63], v[138:141], v[180:183], v[60:63]
	v_mfma_f32_16x16x32_bf16 v[56:59], v[150:153], v[180:183], v[56:59]
	v_mfma_f32_16x16x32_bf16 v[48:51], v[138:141], v[188:191], v[48:51]
	v_mfma_f32_16x16x32_bf16 v[40:43], v[150:153], v[188:191], v[40:43]
	v_mfma_f32_16x16x32_bf16 v[32:35], v[138:141], v[204:207], v[32:35]
	v_mfma_f32_16x16x32_bf16 v[24:27], v[150:153], v[204:207], v[24:27]
	v_mfma_f32_16x16x32_bf16 v[16:19], v[138:141], v[216:219], v[16:19]
	v_mfma_f32_16x16x32_bf16 v[8:11], v[150:153], v[216:219], v[8:11]
	v_mfma_f32_16x16x32_bf16 v[60:63], v[146:149], v[184:187], v[60:63]
	v_mfma_f32_16x16x32_bf16 v[56:59], v[154:157], v[184:187], v[56:59]
	v_mfma_f32_16x16x32_bf16 v[48:51], v[146:149], v[192:195], v[48:51]
	v_mfma_f32_16x16x32_bf16 v[40:43], v[154:157], v[192:195], v[40:43]
	v_mfma_f32_16x16x32_bf16 v[32:35], v[146:149], v[212:215], v[32:35]
	v_mfma_f32_16x16x32_bf16 v[24:27], v[154:157], v[212:215], v[24:27]
	v_mfma_f32_16x16x32_bf16 v[16:19], v[146:149], v[220:223], v[16:19]
	v_mfma_f32_16x16x32_bf16 v[8:11], v[154:157], v[220:223], v[8:11]
	v_mfma_f32_16x16x32_bf16 v[52:55], v[164:167], v[180:183], v[52:55]
	v_mfma_f32_16x16x32_bf16 v[44:47], v[172:175], v[180:183], v[44:47]
	v_mfma_f32_16x16x32_bf16 v[36:39], v[164:167], v[188:191], v[36:39]
	v_mfma_f32_16x16x32_bf16 v[28:31], v[172:175], v[188:191], v[28:31]
	v_mfma_f32_16x16x32_bf16 v[20:23], v[164:167], v[204:207], v[20:23]
	v_mfma_f32_16x16x32_bf16 v[12:15], v[172:175], v[204:207], v[12:15]
	v_mfma_f32_16x16x32_bf16 v[4:7], v[164:167], v[216:219], v[4:7]
	v_mfma_f32_16x16x32_bf16 v[0:3], v[172:175], v[216:219], v[0:3]
	v_mfma_f32_16x16x32_bf16 v[52:55], v[168:171], v[184:187], v[52:55]
	v_mfma_f32_16x16x32_bf16 v[44:47], v[176:179], v[184:187], v[44:47]
	v_mfma_f32_16x16x32_bf16 v[36:39], v[168:171], v[192:195], v[36:39]
	v_mfma_f32_16x16x32_bf16 v[28:31], v[176:179], v[192:195], v[28:31]
	v_mfma_f32_16x16x32_bf16 v[20:23], v[168:171], v[212:215], v[20:23]
	v_mfma_f32_16x16x32_bf16 v[12:15], v[176:179], v[212:215], v[12:15]
	v_mfma_f32_16x16x32_bf16 v[4:7], v[168:171], v[220:223], v[4:7]
	v_mfma_f32_16x16x32_bf16 v[0:3], v[176:179], v[220:223], v[0:3]
	s_add_i32 s47, s47, 2
	s_add_u32 s37, s37, 0x100
	s_addc_u32 s46, s46, 0
	s_mov_b64 s[18:19], s[40:41]
	s_add_u32 s40, s18, 0x100
	s_addc_u32 s41, s19, 0
	s_add_i32 s48, 0, 0x10000
	s_cmp_eq_u32 s47, 40
	s_cselect_b32 s45, s15, s41
	s_cselect_b32 s44, s14, s40
	s_cselect_b32 s43, s17, s46
	s_cselect_b32 s42, s16, s37
	s_add_i32 s49, 0, 0x14000
	v_add_u32_e32 v154, s48, v143
	v_add_u32_e32 v158, s49, v143
	s_cmp_gt_u32 s47, 41
	s_barrier
	s_cbranch_scc0 .Lrot_lbb0_903
	s_and_b64 vcc, exec, s[12:13]
	s_cbranch_vccz .LBB0_906
	s_barrier

.Lrot_lbb0_978:
	ds_read_b128 v[146:149], v145
	ds_read_b128 v[150:153], v145 offset:1024
	ds_read_b128 v[156:159], v145 offset:2048
	ds_read_b128 v[164:167], v145 offset:3072
	v_add_u32_e32 v145, s31, v143
	ds_read_b128 v[168:171], v145
	ds_read_b128 v[172:175], v145 offset:1024
	ds_read_b128 v[176:179], v145 offset:2048
	ds_read_b128 v[180:183], v145 offset:3072
	v_lshl_add_u64 v[236:237], v[138:139], 0, s[48:49]
	s_add_i32 m0, s2, 0xc000
	ds_read_b128 v[184:187], v144
	ds_read_b128 v[188:191], v144 offset:1024
	ds_read_b128 v[192:195], v144 offset:2048
	ds_read_b128 v[204:207], v144 offset:3072
	ds_read_b128 v[212:215], v144 offset:4096
	ds_read_b128 v[216:219], v144 offset:5120
	ds_read_b128 v[220:223], v144 offset:6144
	ds_read_b128 v[232:235], v144 offset:7168
	global_load_lds_dwordx4 v[236:237], off
	v_lshl_add_u64 v[236:237], v[140:141], 0, s[48:49]
	s_add_i32 m0, s2, 0xe000
	s_nop 0
	global_load_lds_dwordx4 v[236:237], off
	s_waitcnt vmcnt(8)
	s_waitcnt lgkmcnt(0)
	s_barrier
	s_waitcnt lgkmcnt(0)
	v_mfma_f32_16x16x32_bf16 v[124:127], v[146:149], v[184:187], v[124:127]
	v_mfma_f32_16x16x32_bf16 v[120:123], v[156:159], v[184:187], v[120:123]
	v_mfma_f32_16x16x32_bf16 v[108:111], v[146:149], v[192:195], v[108:111]
	v_mfma_f32_16x16x32_bf16 v[104:107], v[156:159], v[192:195], v[104:107]
	v_mfma_f32_16x16x32_bf16 v[92:95], v[146:149], v[212:215], v[92:95]
	v_mfma_f32_16x16x32_bf16 v[88:91], v[156:159], v[212:215], v[88:91]
	v_mfma_f32_16x16x32_bf16 v[76:79], v[146:149], v[220:223], v[76:79]
	v_mfma_f32_16x16x32_bf16 v[72:75], v[156:159], v[220:223], v[72:75]
	v_mfma_f32_16x16x32_bf16 v[124:127], v[150:153], v[188:191], v[124:127]
	v_mfma_f32_16x16x32_bf16 v[120:123], v[164:167], v[188:191], v[120:123]
	v_mfma_f32_16x16x32_bf16 v[108:111], v[150:153], v[204:207], v[108:111]
	v_mfma_f32_16x16x32_bf16 v[104:107], v[164:167], v[204:207], v[104:107]
	v_mfma_f32_16x16x32_bf16 v[92:95], v[150:153], v[216:219], v[92:95]
	v_mfma_f32_16x16x32_bf16 v[88:91], v[164:167], v[216:219], v[88:91]
	v_mfma_f32_16x16x32_bf16 v[76:79], v[150:153], v[232:235], v[76:79]
	v_mfma_f32_16x16x32_bf16 v[72:75], v[164:167], v[232:235], v[72:75]
	v_mfma_f32_16x16x32_bf16 v[116:119], v[168:171], v[184:187], v[116:119]
	v_mfma_f32_16x16x32_bf16 v[112:115], v[176:179], v[184:187], v[112:115]
	v_mfma_f32_16x16x32_bf16 v[100:103], v[168:171], v[192:195], v[100:103]
	v_mfma_f32_16x16x32_bf16 v[96:99], v[176:179], v[192:195], v[96:99]
	v_mfma_f32_16x16x32_bf16 v[84:87], v[168:171], v[212:215], v[84:87]
	v_mfma_f32_16x16x32_bf16 v[80:83], v[176:179], v[212:215], v[80:83]
	v_mfma_f32_16x16x32_bf16 v[68:71], v[168:171], v[220:223], v[68:71]
	v_mfma_f32_16x16x32_bf16 v[64:67], v[176:179], v[220:223], v[64:67]
	v_mfma_f32_16x16x32_bf16 v[116:119], v[172:175], v[188:191], v[116:119]
	v_mfma_f32_16x16x32_bf16 v[112:115], v[180:183], v[188:191], v[112:115]
	v_mfma_f32_16x16x32_bf16 v[100:103], v[172:175], v[204:207], v[100:103]
	v_mfma_f32_16x16x32_bf16 v[96:99], v[180:183], v[204:207], v[96:99]
	v_mfma_f32_16x16x32_bf16 v[84:87], v[172:175], v[216:219], v[84:87]
	v_mfma_f32_16x16x32_bf16 v[80:83], v[180:183], v[216:219], v[80:83]
	v_mfma_f32_16x16x32_bf16 v[68:71], v[172:175], v[232:235], v[68:71]
	v_mfma_f32_16x16x32_bf16 v[64:67], v[180:183], v[232:235], v[64:67]
	s_barrier
	s_add_i32 s34, s37, s1
	v_lshl_add_u64 v[236:237], s[50:51], 0, v[196:197]
	s_mov_b32 m0, s34
	ds_read_b128 v[184:187], v144 offset:16384
	ds_read_b128 v[188:191], v144 offset:17408
	ds_read_b128 v[192:195], v144 offset:18432
	ds_read_b128 v[204:207], v144 offset:19456
	ds_read_b128 v[212:215], v144 offset:20480
	ds_read_b128 v[216:219], v144 offset:21504
	ds_read_b128 v[220:223], v144 offset:22528
	ds_read_b128 v[232:235], v144 offset:23552
	global_load_lds_dwordx4 v[236:237], off
	s_add_i32 m0, s34, 0x2000
	s_add_u32 s34, s50, 0x40000
	v_lshl_add_u64 v[238:239], s[50:51], 0, v[132:133]
	s_addc_u32 s35, s51, 0
	s_add_i32 s31, s31, s1
	global_load_lds_dwordx4 v[238:239], off
	v_lshl_add_u64 v[240:241], s[34:35], 0, v[196:197]
	s_mov_b32 m0, s31
	v_lshl_add_u64 v[242:243], s[52:53], 0, v[130:131]
	global_load_lds_dwordx4 v[240:241], off
	v_lshl_add_u64 v[240:241], s[34:35], 0, v[132:133]
	s_add_i32 m0, s31, 0x2000
	s_nop 0
	global_load_lds_dwordx4 v[240:241], off
	v_lshl_add_u64 v[240:241], s[52:53], 0, v[128:129]
	s_mov_b32 m0, s2
	s_nop 0
	global_load_lds_dwordx4 v[240:241], off
	s_mov_b32 m0, s19
	s_nop 0
	global_load_lds_dwordx4 v[242:243], off
	s_waitcnt vmcnt(8)
	s_waitcnt lgkmcnt(0)
	s_barrier
	s_waitcnt lgkmcnt(0)
	v_mfma_f32_16x16x32_bf16 v[60:63], v[146:149], v[184:187], v[60:63]
	v_mfma_f32_16x16x32_bf16 v[56:59], v[156:159], v[184:187], v[56:59]
	v_mfma_f32_16x16x32_bf16 v[44:47], v[146:149], v[192:195], v[44:47]
	v_mfma_f32_16x16x32_bf16 v[40:43], v[156:159], v[192:195], v[40:43]
	v_mfma_f32_16x16x32_bf16 v[28:31], v[146:149], v[212:215], v[28:31]
	v_mfma_f32_16x16x32_bf16 v[24:27], v[156:159], v[212:215], v[24:27]
	v_mfma_f32_16x16x32_bf16 v[12:15], v[146:149], v[220:223], v[12:15]
	v_mfma_f32_16x16x32_bf16 v[8:11], v[156:159], v[220:223], v[8:11]
	v_mfma_f32_16x16x32_bf16 v[60:63], v[150:153], v[188:191], v[60:63]
	v_mfma_f32_16x16x32_bf16 v[56:59], v[164:167], v[188:191], v[56:59]
	v_mfma_f32_16x16x32_bf16 v[44:47], v[150:153], v[204:207], v[44:47]
	v_mfma_f32_16x16x32_bf16 v[40:43], v[164:167], v[204:207], v[40:43]
	v_mfma_f32_16x16x32_bf16 v[28:31], v[150:153], v[216:219], v[28:31]
	v_mfma_f32_16x16x32_bf16 v[24:27], v[164:167], v[216:219], v[24:27]
	v_mfma_f32_16x16x32_bf16 v[12:15], v[150:153], v[232:235], v[12:15]
	v_mfma_f32_16x16x32_bf16 v[8:11], v[164:167], v[232:235], v[8:11]
	v_mfma_f32_16x16x32_bf16 v[52:55], v[168:171], v[184:187], v[52:55]
	v_mfma_f32_16x16x32_bf16 v[48:51], v[176:179], v[184:187], v[48:51]
	v_mfma_f32_16x16x32_bf16 v[36:39], v[168:171], v[192:195], v[36:39]
	v_mfma_f32_16x16x32_bf16 v[32:35], v[176:179], v[192:195], v[32:35]
	v_mfma_f32_16x16x32_bf16 v[20:23], v[168:171], v[212:215], v[20:23]
	v_mfma_f32_16x16x32_bf16 v[16:19], v[176:179], v[212:215], v[16:19]
	v_mfma_f32_16x16x32_bf16 v[4:7], v[168:171], v[220:223], v[4:7]
	v_mfma_f32_16x16x32_bf16 v[0:3], v[176:179], v[220:223], v[0:3]
	v_mfma_f32_16x16x32_bf16 v[52:55], v[172:175], v[188:191], v[52:55]
	v_mfma_f32_16x16x32_bf16 v[48:51], v[180:183], v[188:191], v[48:51]
	v_mfma_f32_16x16x32_bf16 v[36:39], v[172:175], v[204:207], v[36:39]
	v_mfma_f32_16x16x32_bf16 v[32:35], v[180:183], v[204:207], v[32:35]
	v_mfma_f32_16x16x32_bf16 v[20:23], v[172:175], v[216:219], v[20:23]
	v_mfma_f32_16x16x32_bf16 v[16:19], v[180:183], v[216:219], v[16:19]
	v_mfma_f32_16x16x32_bf16 v[4:7], v[172:175], v[232:235], v[4:7]
	v_mfma_f32_16x16x32_bf16 v[0:3], v[180:183], v[232:235], v[0:3]
	s_barrier
	s_add_i32 s31, 0, 0x18000
	v_add_u32_e32 v145, s31, v143
	s_add_i32 s36, 0, 0x1c000
	ds_read_b128 v[146:149], v145
	ds_read_b128 v[150:153], v145 offset:1024
	ds_read_b128 v[156:159], v145 offset:2048
	ds_read_b128 v[164:167], v145 offset:3072
	v_add_u32_e32 v145, s36, v143
	ds_read_b128 v[168:171], v145
	ds_read_b128 v[172:175], v145 offset:1024
	ds_read_b128 v[176:179], v145 offset:2048
	ds_read_b128 v[180:183], v145 offset:3072
	s_add_u32 s34, s52, 0x40000
	s_addc_u32 s35, s53, 0
	s_mov_b32 m0, s20
	v_lshl_add_u64 v[244:245], s[34:35], 0, v[128:129]
	ds_read_b128 v[184:187], v144 offset:32768
	ds_read_b128 v[188:191], v144 offset:33792
	ds_read_b128 v[192:195], v144 offset:34816
	ds_read_b128 v[204:207], v144 offset:35840
	ds_read_b128 v[212:215], v144 offset:36864
	ds_read_b128 v[216:219], v144 offset:37888
	ds_read_b128 v[220:223], v144 offset:38912
	ds_read_b128 v[232:235], v144 offset:39936
	global_load_lds_dwordx4 v[244:245], off
	v_lshl_add_u64 v[244:245], s[34:35], 0, v[130:131]
	s_mov_b32 m0, s21
	s_nop 0
	global_load_lds_dwordx4 v[244:245], off
	s_waitcnt vmcnt(8)
	s_waitcnt lgkmcnt(0)
	s_barrier
	s_waitcnt lgkmcnt(0)
	v_mfma_f32_16x16x32_bf16 v[124:127], v[146:149], v[184:187], v[124:127]
	v_mfma_f32_16x16x32_bf16 v[120:123], v[156:159], v[184:187], v[120:123]
	v_mfma_f32_16x16x32_bf16 v[108:111], v[146:149], v[192:195], v[108:111]
	v_mfma_f32_16x16x32_bf16 v[104:107], v[156:159], v[192:195], v[104:107]
	v_mfma_f32_16x16x32_bf16 v[92:95], v[146:149], v[212:215], v[92:95]
	v_mfma_f32_16x16x32_bf16 v[88:91], v[156:159], v[212:215], v[88:91]
	v_mfma_f32_16x16x32_bf16 v[76:79], v[146:149], v[220:223], v[76:79]
	v_mfma_f32_16x16x32_bf16 v[72:75], v[156:159], v[220:223], v[72:75]
	v_mfma_f32_16x16x32_bf16 v[124:127], v[150:153], v[188:191], v[124:127]
	v_mfma_f32_16x16x32_bf16 v[120:123], v[164:167], v[188:191], v[120:123]
	v_mfma_f32_16x16x32_bf16 v[108:111], v[150:153], v[204:207], v[108:111]
	v_mfma_f32_16x16x32_bf16 v[104:107], v[164:167], v[204:207], v[104:107]
	v_mfma_f32_16x16x32_bf16 v[92:95], v[150:153], v[216:219], v[92:95]
	v_mfma_f32_16x16x32_bf16 v[88:91], v[164:167], v[216:219], v[88:91]
	v_mfma_f32_16x16x32_bf16 v[76:79], v[150:153], v[232:235], v[76:79]
	v_mfma_f32_16x16x32_bf16 v[72:75], v[164:167], v[232:235], v[72:75]
	v_mfma_f32_16x16x32_bf16 v[116:119], v[168:171], v[184:187], v[116:119]
	v_mfma_f32_16x16x32_bf16 v[112:115], v[176:179], v[184:187], v[112:115]
	v_mfma_f32_16x16x32_bf16 v[100:103], v[168:171], v[192:195], v[100:103]
	v_mfma_f32_16x16x32_bf16 v[96:99], v[176:179], v[192:195], v[96:99]
	v_mfma_f32_16x16x32_bf16 v[84:87], v[168:171], v[212:215], v[84:87]
	v_mfma_f32_16x16x32_bf16 v[80:83], v[176:179], v[212:215], v[80:83]
	v_mfma_f32_16x16x32_bf16 v[68:71], v[168:171], v[220:223], v[68:71]
	v_mfma_f32_16x16x32_bf16 v[64:67], v[176:179], v[220:223], v[64:67]
	v_mfma_f32_16x16x32_bf16 v[116:119], v[172:175], v[188:191], v[116:119]
	v_mfma_f32_16x16x32_bf16 v[112:115], v[180:183], v[188:191], v[112:115]
	v_mfma_f32_16x16x32_bf16 v[100:103], v[172:175], v[204:207], v[100:103]
	v_mfma_f32_16x16x32_bf16 v[96:99], v[180:183], v[204:207], v[96:99]
	v_mfma_f32_16x16x32_bf16 v[84:87], v[172:175], v[216:219], v[84:87]
	v_mfma_f32_16x16x32_bf16 v[80:83], v[180:183], v[216:219], v[80:83]
	v_mfma_f32_16x16x32_bf16 v[68:71], v[172:175], v[232:235], v[68:71]
	v_mfma_f32_16x16x32_bf16 v[64:67], v[180:183], v[232:235], v[64:67]
	s_barrier
	s_add_i32 s31, s31, s1
	v_lshl_add_u64 v[236:237], v[236:237], 0, s[10:11]
	s_mov_b32 m0, s31
	ds_read_b128 v[184:187], v144 offset:49152
	ds_read_b128 v[188:191], v144 offset:50176
	ds_read_b128 v[192:195], v144 offset:51200
	ds_read_b128 v[204:207], v144 offset:52224
	ds_read_b128 v[212:215], v144 offset:53248
	ds_read_b128 v[216:219], v144 offset:54272
	ds_read_b128 v[220:223], v144 offset:55296
	ds_read_b128 v[232:235], v144 offset:56320
	global_load_lds_dwordx4 v[236:237], off
	s_add_i32 m0, s31, 0x2000
	s_add_u32 s34, s50, 0x40080
	v_lshl_add_u64 v[236:237], v[238:239], 0, s[10:11]
	s_addc_u32 s35, s51, 0
	s_add_i32 s31, s36, s1
	global_load_lds_dwordx4 v[236:237], off
	v_lshl_add_u64 v[236:237], s[34:35], 0, v[196:197]
	s_mov_b32 m0, s31
	s_nop 0
	global_load_lds_dwordx4 v[236:237], off
	v_lshl_add_u64 v[236:237], s[34:35], 0, v[132:133]
	s_add_i32 m0, s31, 0x2000
	s_nop 0
	global_load_lds_dwordx4 v[236:237], off
	v_lshl_add_u64 v[236:237], v[240:241], 0, s[10:11]
	s_mov_b32 m0, s22
	s_nop 0
	global_load_lds_dwordx4 v[236:237], off
	v_lshl_add_u64 v[236:237], v[242:243], 0, s[10:11]
	s_mov_b32 m0, s23
	s_nop 0
	global_load_lds_dwordx4 v[236:237], off
	s_waitcnt vmcnt(8)
	s_waitcnt lgkmcnt(0)
	s_barrier
	s_waitcnt lgkmcnt(0)
	v_mfma_f32_16x16x32_bf16 v[60:63], v[146:149], v[184:187], v[60:63]
	v_mfma_f32_16x16x32_bf16 v[56:59], v[156:159], v[184:187], v[56:59]
	v_mfma_f32_16x16x32_bf16 v[44:47], v[146:149], v[192:195], v[44:47]
	v_mfma_f32_16x16x32_bf16 v[40:43], v[156:159], v[192:195], v[40:43]
	v_mfma_f32_16x16x32_bf16 v[28:31], v[146:149], v[212:215], v[28:31]
	v_mfma_f32_16x16x32_bf16 v[24:27], v[156:159], v[212:215], v[24:27]
	v_mfma_f32_16x16x32_bf16 v[12:15], v[146:149], v[220:223], v[12:15]
	v_mfma_f32_16x16x32_bf16 v[8:11], v[156:159], v[220:223], v[8:11]
	v_mfma_f32_16x16x32_bf16 v[60:63], v[150:153], v[188:191], v[60:63]
	v_mfma_f32_16x16x32_bf16 v[56:59], v[164:167], v[188:191], v[56:59]
	v_mfma_f32_16x16x32_bf16 v[44:47], v[150:153], v[204:207], v[44:47]
	v_mfma_f32_16x16x32_bf16 v[40:43], v[164:167], v[204:207], v[40:43]
	v_mfma_f32_16x16x32_bf16 v[28:31], v[150:153], v[216:219], v[28:31]
	v_mfma_f32_16x16x32_bf16 v[24:27], v[164:167], v[216:219], v[24:27]
	v_mfma_f32_16x16x32_bf16 v[12:15], v[150:153], v[232:235], v[12:15]
	v_mfma_f32_16x16x32_bf16 v[8:11], v[164:167], v[232:235], v[8:11]
	v_mfma_f32_16x16x32_bf16 v[52:55], v[168:171], v[184:187], v[52:55]
	v_mfma_f32_16x16x32_bf16 v[48:51], v[176:179], v[184:187], v[48:51]
	v_mfma_f32_16x16x32_bf16 v[36:39], v[168:171], v[192:195], v[36:39]
	v_mfma_f32_16x16x32_bf16 v[32:35], v[176:179], v[192:195], v[32:35]
	v_mfma_f32_16x16x32_bf16 v[20:23], v[168:171], v[212:215], v[20:23]
	v_mfma_f32_16x16x32_bf16 v[16:19], v[176:179], v[212:215], v[16:19]
	v_mfma_f32_16x16x32_bf16 v[4:7], v[168:171], v[220:223], v[4:7]
	v_mfma_f32_16x16x32_bf16 v[0:3], v[176:179], v[220:223], v[0:3]
	v_mfma_f32_16x16x32_bf16 v[52:55], v[172:175], v[188:191], v[52:55]
	v_mfma_f32_16x16x32_bf16 v[48:51], v[180:183], v[188:191], v[48:51]
	v_mfma_f32_16x16x32_bf16 v[36:39], v[172:175], v[204:207], v[36:39]
	v_mfma_f32_16x16x32_bf16 v[32:35], v[180:183], v[204:207], v[32:35]
	v_mfma_f32_16x16x32_bf16 v[20:23], v[172:175], v[216:219], v[20:23]
	v_mfma_f32_16x16x32_bf16 v[16:19], v[180:183], v[216:219], v[16:19]
	v_mfma_f32_16x16x32_bf16 v[4:7], v[172:175], v[232:235], v[4:7]
	v_mfma_f32_16x16x32_bf16 v[0:3], v[180:183], v[232:235], v[0:3]
	s_add_i32 s30, s30, 2
	s_add_u32 s48, s48, 0x100
	s_addc_u32 s49, s49, 0
	s_add_u32 s31, s6, s48
	s_addc_u32 s34, s7, s49
	s_add_u32 s31, s31, 0x100
	s_addc_u32 s34, s34, 0
	s_add_u32 s35, s26, s48
	s_addc_u32 s36, s27, s49
	s_add_i32 s37, 0, 0x10000
	s_cmpk_eq_i32 s48, 0x700
	s_cselect_b32 s53, s13, s34
	s_cselect_b32 s52, s28, s31
	v_add_u32_e32 v145, s37, v143
	s_cselect_b32 s51, s9, s36
	s_cselect_b32 s50, s29, s35
	s_add_i32 s31, 0, 0x14000
	s_cmp_gt_u32 s30, 13
	s_barrier
	s_cbranch_scc0 .Lrot_lbb0_978
	s_add_u32 s48, s26, 0xffffff00
	s_addc_u32 s49, s27, -1
	s_andn2_b64 vcc, exec, s[40:41]
	s_cbranch_vccnz .LBB0_981
	v_mov_b32_e32 v0, 0
	s_mov_b32 s42, s8
	s_mov_b32 s18, s12
	s_mov_b64 s[6:7], s[46:47]
	s_mov_b32 s24, s25
	v_mov_b32_e32 v1, v0
	v_mov_b32_e32 v2, v0
	v_mov_b32_e32 v3, v0
	v_mov_b32_e32 v4, v0
	v_mov_b32_e32 v5, v0
	v_mov_b32_e32 v6, v0
	v_mov_b32_e32 v7, v0
	v_mov_b32_e32 v16, v0
	v_mov_b32_e32 v17, v0
	v_mov_b32_e32 v18, v0
	v_mov_b32_e32 v19, v0
	v_mov_b32_e32 v20, v0
	v_mov_b32_e32 v21, v0
	v_mov_b32_e32 v22, v0
	v_mov_b32_e32 v23, v0
	v_mov_b32_e32 v32, v0
	v_mov_b32_e32 v33, v0
	v_mov_b32_e32 v34, v0
	v_mov_b32_e32 v35, v0
	v_mov_b32_e32 v36, v0
	v_mov_b32_e32 v37, v0
	v_mov_b32_e32 v38, v0
	v_mov_b32_e32 v39, v0
	v_mov_b32_e32 v48, v0
	v_mov_b32_e32 v49, v0
	v_mov_b32_e32 v50, v0
	v_mov_b32_e32 v51, v0
	v_mov_b32_e32 v52, v0
	v_mov_b32_e32 v53, v0
	v_mov_b32_e32 v54, v0
	v_mov_b32_e32 v55, v0
	v_mov_b32_e32 v8, v0
	v_mov_b32_e32 v9, v0
	v_mov_b32_e32 v10, v0
	v_mov_b32_e32 v11, v0
	v_mov_b32_e32 v12, v0
	v_mov_b32_e32 v13, v0
	v_mov_b32_e32 v14, v0
	v_mov_b32_e32 v15, v0
	v_mov_b32_e32 v24, v0
	v_mov_b32_e32 v25, v0
	v_mov_b32_e32 v26, v0
	v_mov_b32_e32 v27, v0
	v_mov_b32_e32 v28, v0
	v_mov_b32_e32 v29, v0
	v_mov_b32_e32 v30, v0
	v_mov_b32_e32 v31, v0
	v_mov_b32_e32 v40, v0
	v_mov_b32_e32 v41, v0
	v_mov_b32_e32 v42, v0
	v_mov_b32_e32 v43, v0
	v_mov_b32_e32 v44, v0
	v_mov_b32_e32 v45, v0
	v_mov_b32_e32 v46, v0
	v_mov_b32_e32 v47, v0
	v_mov_b32_e32 v56, v0
	v_mov_b32_e32 v57, v0
	v_mov_b32_e32 v58, v0
	v_mov_b32_e32 v59, v0
	v_mov_b32_e32 v60, v0
	v_mov_b32_e32 v61, v0
	v_mov_b32_e32 v62, v0
	v_mov_b32_e32 v63, v0
	v_mov_b32_e32 v64, v0
	v_mov_b32_e32 v65, v0
	v_mov_b32_e32 v66, v0
	v_mov_b32_e32 v67, v0
	v_mov_b32_e32 v68, v0
	v_mov_b32_e32 v69, v0
	v_mov_b32_e32 v70, v0
	v_mov_b32_e32 v71, v0
	v_mov_b32_e32 v80, v0
	v_mov_b32_e32 v81, v0
	v_mov_b32_e32 v82, v0
	v_mov_b32_e32 v83, v0
	v_mov_b32_e32 v84, v0
	v_mov_b32_e32 v85, v0
	v_mov_b32_e32 v86, v0
	v_mov_b32_e32 v87, v0
	v_mov_b32_e32 v96, v0
	v_mov_b32_e32 v97, v0
	v_mov_b32_e32 v98, v0
	v_mov_b32_e32 v99, v0
	v_mov_b32_e32 v100, v0
	v_mov_b32_e32 v101, v0
	v_mov_b32_e32 v102, v0
	v_mov_b32_e32 v103, v0
	v_mov_b32_e32 v112, v0
	v_mov_b32_e32 v113, v0
	v_mov_b32_e32 v114, v0
	v_mov_b32_e32 v115, v0
	v_mov_b32_e32 v116, v0
	v_mov_b32_e32 v117, v0
	v_mov_b32_e32 v118, v0
	v_mov_b32_e32 v119, v0
	v_mov_b32_e32 v72, v0
	v_mov_b32_e32 v73, v0
	v_mov_b32_e32 v74, v0
	v_mov_b32_e32 v75, v0
	v_mov_b32_e32 v76, v0
	v_mov_b32_e32 v77, v0
	v_mov_b32_e32 v78, v0
	v_mov_b32_e32 v79, v0
	v_mov_b32_e32 v88, v0
	v_mov_b32_e32 v89, v0
	v_mov_b32_e32 v90, v0
	v_mov_b32_e32 v91, v0
	v_mov_b32_e32 v92, v0
	v_mov_b32_e32 v93, v0
	v_mov_b32_e32 v94, v0
	v_mov_b32_e32 v95, v0
	v_mov_b32_e32 v104, v0
	v_mov_b32_e32 v105, v0
	v_mov_b32_e32 v106, v0
	v_mov_b32_e32 v107, v0
	v_mov_b32_e32 v108, v0
	v_mov_b32_e32 v109, v0
	v_mov_b32_e32 v110, v0
	v_mov_b32_e32 v111, v0
	v_mov_b32_e32 v120, v0
	v_mov_b32_e32 v121, v0
	v_mov_b32_e32 v122, v0
	v_mov_b32_e32 v123, v0
	v_mov_b32_e32 v124, v0
	v_mov_b32_e32 v125, v0
	v_mov_b32_e32 v126, v0
	v_mov_b32_e32 v127, v0
	s_branch .LBB0_982

.Lrot_lbb0_1033:
	ds_read_b128 v[148:151], v147
	ds_read_b128 v[152:155], v147 offset:1024
	ds_read_b128 v[156:159], v147 offset:2048
	ds_read_b128 v[164:167], v147 offset:3072
	v_add_u32_e32 v147, s35, v144
	ds_read_b128 v[168:171], v147
	ds_read_b128 v[172:175], v147 offset:1024
	ds_read_b128 v[176:179], v147 offset:2048
	ds_read_b128 v[180:183], v147 offset:3072
	v_lshl_add_u64 v[236:237], v[138:139], 0, s[48:49]
	s_add_i32 m0, s7, 0xc000
	ds_read_b128 v[184:187], v145
	ds_read_b128 v[188:191], v145 offset:1024
	ds_read_b128 v[192:195], v145 offset:2048
	ds_read_b128 v[204:207], v145 offset:3072
	ds_read_b128 v[212:215], v145 offset:4096
	ds_read_b128 v[216:219], v145 offset:5120
	ds_read_b128 v[220:223], v145 offset:6144
	ds_read_b128 v[232:235], v145 offset:7168
	global_load_lds_dwordx4 v[236:237], off
	v_lshl_add_u64 v[236:237], v[140:141], 0, s[48:49]
	s_add_i32 m0, s7, 0xe000
	s_nop 0
	global_load_lds_dwordx4 v[236:237], off
	s_waitcnt vmcnt(8)
	s_waitcnt lgkmcnt(0)
	s_barrier
	s_waitcnt lgkmcnt(0)
	v_mfma_f32_16x16x32_bf16 v[76:79], v[148:151], v[184:187], v[76:79]
	v_mfma_f32_16x16x32_bf16 v[72:75], v[156:159], v[184:187], v[72:75]
	v_mfma_f32_16x16x32_bf16 v[116:119], v[148:151], v[192:195], v[116:119]
	v_mfma_f32_16x16x32_bf16 v[112:115], v[156:159], v[192:195], v[112:115]
	v_mfma_f32_16x16x32_bf16 v[88:91], v[148:151], v[212:215], v[88:91]
	v_mfma_f32_16x16x32_bf16 v[84:87], v[156:159], v[212:215], v[84:87]
	v_mfma_f32_16x16x32_bf16 v[108:111], v[148:151], v[220:223], v[108:111]
	v_mfma_f32_16x16x32_bf16 v[104:107], v[156:159], v[220:223], v[104:107]
	v_mfma_f32_16x16x32_bf16 v[76:79], v[152:155], v[188:191], v[76:79]
	v_mfma_f32_16x16x32_bf16 v[72:75], v[164:167], v[188:191], v[72:75]
	v_mfma_f32_16x16x32_bf16 v[116:119], v[152:155], v[204:207], v[116:119]
	v_mfma_f32_16x16x32_bf16 v[112:115], v[164:167], v[204:207], v[112:115]
	v_mfma_f32_16x16x32_bf16 v[88:91], v[152:155], v[216:219], v[88:91]
	v_mfma_f32_16x16x32_bf16 v[84:87], v[164:167], v[216:219], v[84:87]
	v_mfma_f32_16x16x32_bf16 v[108:111], v[152:155], v[232:235], v[108:111]
	v_mfma_f32_16x16x32_bf16 v[104:107], v[164:167], v[232:235], v[104:107]
	v_mfma_f32_16x16x32_bf16 v[96:99], v[168:171], v[184:187], v[96:99]
	v_mfma_f32_16x16x32_bf16 v[92:95], v[176:179], v[184:187], v[92:95]
	v_mfma_f32_16x16x32_bf16 v[124:127], v[168:171], v[192:195], v[124:127]
	v_mfma_f32_16x16x32_bf16 v[120:123], v[176:179], v[192:195], v[120:123]
	v_mfma_f32_16x16x32_bf16 v[100:103], v[168:171], v[212:215], v[100:103]
	v_mfma_f32_16x16x32_bf16 v[80:83], v[176:179], v[212:215], v[80:83]
	v_mfma_f32_16x16x32_bf16 v[68:71], v[168:171], v[220:223], v[68:71]
	v_mfma_f32_16x16x32_bf16 v[64:67], v[176:179], v[220:223], v[64:67]
	v_mfma_f32_16x16x32_bf16 v[96:99], v[172:175], v[188:191], v[96:99]
	v_mfma_f32_16x16x32_bf16 v[92:95], v[180:183], v[188:191], v[92:95]
	v_mfma_f32_16x16x32_bf16 v[124:127], v[172:175], v[204:207], v[124:127]
	v_mfma_f32_16x16x32_bf16 v[120:123], v[180:183], v[204:207], v[120:123]
	v_mfma_f32_16x16x32_bf16 v[100:103], v[172:175], v[216:219], v[100:103]
	v_mfma_f32_16x16x32_bf16 v[80:83], v[180:183], v[216:219], v[80:83]
	v_mfma_f32_16x16x32_bf16 v[68:71], v[172:175], v[232:235], v[68:71]
	v_mfma_f32_16x16x32_bf16 v[64:67], v[180:183], v[232:235], v[64:67]
	s_barrier
	s_add_i32 s36, s58, s9
	v_lshl_add_u64 v[236:237], s[50:51], 0, v[196:197]
	s_mov_b32 m0, s36
	ds_read_b128 v[184:187], v145 offset:16384
	ds_read_b128 v[188:191], v145 offset:17408
	ds_read_b128 v[192:195], v145 offset:18432
	ds_read_b128 v[204:207], v145 offset:19456
	ds_read_b128 v[212:215], v145 offset:20480
	ds_read_b128 v[216:219], v145 offset:21504
	ds_read_b128 v[220:223], v145 offset:22528
	ds_read_b128 v[232:235], v145 offset:23552
	global_load_lds_dwordx4 v[236:237], off
	s_add_i32 m0, s36, 0x2000
	s_add_u32 s36, s50, 0x40000
	v_lshl_add_u64 v[238:239], s[50:51], 0, v[132:133]
	s_addc_u32 s37, s51, 0
	s_add_i32 s35, s35, s9
	global_load_lds_dwordx4 v[238:239], off
	v_lshl_add_u64 v[240:241], s[36:37], 0, v[196:197]
	s_mov_b32 m0, s35
	v_lshl_add_u64 v[242:243], s[52:53], 0, v[130:131]
	global_load_lds_dwordx4 v[240:241], off
	v_lshl_add_u64 v[240:241], s[36:37], 0, v[132:133]
	s_add_i32 m0, s35, 0x2000
	s_nop 0
	global_load_lds_dwordx4 v[240:241], off
	v_lshl_add_u64 v[240:241], s[52:53], 0, v[128:129]
	s_mov_b32 m0, s7
	s_nop 0
	global_load_lds_dwordx4 v[240:241], off
	s_mov_b32 m0, s20
	s_nop 0
	global_load_lds_dwordx4 v[242:243], off
	s_waitcnt vmcnt(8)
	s_waitcnt lgkmcnt(0)
	s_barrier
	s_waitcnt lgkmcnt(0)
	v_mfma_f32_16x16x32_bf16 v[60:63], v[148:151], v[184:187], v[60:63]
	v_mfma_f32_16x16x32_bf16 v[56:59], v[156:159], v[184:187], v[56:59]
	v_mfma_f32_16x16x32_bf16 v[44:47], v[148:151], v[192:195], v[44:47]
	v_mfma_f32_16x16x32_bf16 v[40:43], v[156:159], v[192:195], v[40:43]
	v_mfma_f32_16x16x32_bf16 v[28:31], v[148:151], v[212:215], v[28:31]
	v_mfma_f32_16x16x32_bf16 v[24:27], v[156:159], v[212:215], v[24:27]
	v_mfma_f32_16x16x32_bf16 v[12:15], v[148:151], v[220:223], v[12:15]
	v_mfma_f32_16x16x32_bf16 v[8:11], v[156:159], v[220:223], v[8:11]
	v_mfma_f32_16x16x32_bf16 v[60:63], v[152:155], v[188:191], v[60:63]
	v_mfma_f32_16x16x32_bf16 v[56:59], v[164:167], v[188:191], v[56:59]
	v_mfma_f32_16x16x32_bf16 v[44:47], v[152:155], v[204:207], v[44:47]
	v_mfma_f32_16x16x32_bf16 v[40:43], v[164:167], v[204:207], v[40:43]
	v_mfma_f32_16x16x32_bf16 v[28:31], v[152:155], v[216:219], v[28:31]
	v_mfma_f32_16x16x32_bf16 v[24:27], v[164:167], v[216:219], v[24:27]
	v_mfma_f32_16x16x32_bf16 v[12:15], v[152:155], v[232:235], v[12:15]
	v_mfma_f32_16x16x32_bf16 v[8:11], v[164:167], v[232:235], v[8:11]
	v_mfma_f32_16x16x32_bf16 v[52:55], v[168:171], v[184:187], v[52:55]
	v_mfma_f32_16x16x32_bf16 v[48:51], v[176:179], v[184:187], v[48:51]
	v_mfma_f32_16x16x32_bf16 v[36:39], v[168:171], v[192:195], v[36:39]
	v_mfma_f32_16x16x32_bf16 v[32:35], v[176:179], v[192:195], v[32:35]
	v_mfma_f32_16x16x32_bf16 v[20:23], v[168:171], v[212:215], v[20:23]
	v_mfma_f32_16x16x32_bf16 v[16:19], v[176:179], v[212:215], v[16:19]
	v_mfma_f32_16x16x32_bf16 v[4:7], v[168:171], v[220:223], v[4:7]
	v_mfma_f32_16x16x32_bf16 v[0:3], v[176:179], v[220:223], v[0:3]
	v_mfma_f32_16x16x32_bf16 v[52:55], v[172:175], v[188:191], v[52:55]
	v_mfma_f32_16x16x32_bf16 v[48:51], v[180:183], v[188:191], v[48:51]
	v_mfma_f32_16x16x32_bf16 v[36:39], v[172:175], v[204:207], v[36:39]
	v_mfma_f32_16x16x32_bf16 v[32:35], v[180:183], v[204:207], v[32:35]
	v_mfma_f32_16x16x32_bf16 v[20:23], v[172:175], v[216:219], v[20:23]
	v_mfma_f32_16x16x32_bf16 v[16:19], v[180:183], v[216:219], v[16:19]
	v_mfma_f32_16x16x32_bf16 v[4:7], v[172:175], v[232:235], v[4:7]
	v_mfma_f32_16x16x32_bf16 v[0:3], v[180:183], v[232:235], v[0:3]
	s_barrier
	s_add_i32 s35, 0, 0x18000
	v_add_u32_e32 v147, s35, v144
	s_add_i32 s43, 0, 0x1c000
	ds_read_b128 v[148:151], v147
	ds_read_b128 v[152:155], v147 offset:1024
	ds_read_b128 v[156:159], v147 offset:2048
	ds_read_b128 v[164:167], v147 offset:3072
	v_add_u32_e32 v147, s43, v144
	ds_read_b128 v[168:171], v147
	ds_read_b128 v[172:175], v147 offset:1024
	ds_read_b128 v[176:179], v147 offset:2048
	ds_read_b128 v[180:183], v147 offset:3072
	s_add_u32 s36, s52, 0x40000
	s_addc_u32 s37, s53, 0
	s_mov_b32 m0, s21
	v_lshl_add_u64 v[244:245], s[36:37], 0, v[128:129]
	ds_read_b128 v[184:187], v145 offset:32768
	ds_read_b128 v[188:191], v145 offset:33792
	ds_read_b128 v[192:195], v145 offset:34816
	ds_read_b128 v[204:207], v145 offset:35840
	ds_read_b128 v[212:215], v145 offset:36864
	ds_read_b128 v[216:219], v145 offset:37888
	ds_read_b128 v[220:223], v145 offset:38912
	ds_read_b128 v[232:235], v145 offset:39936
	global_load_lds_dwordx4 v[244:245], off
	v_lshl_add_u64 v[244:245], s[36:37], 0, v[130:131]
	s_mov_b32 m0, s22
	s_nop 0
	global_load_lds_dwordx4 v[244:245], off
	s_waitcnt vmcnt(8)
	s_waitcnt lgkmcnt(0)
	s_barrier
	s_waitcnt lgkmcnt(0)
	v_mfma_f32_16x16x32_bf16 v[76:79], v[148:151], v[184:187], v[76:79]
	v_mfma_f32_16x16x32_bf16 v[72:75], v[156:159], v[184:187], v[72:75]
	v_mfma_f32_16x16x32_bf16 v[116:119], v[148:151], v[192:195], v[116:119]
	v_mfma_f32_16x16x32_bf16 v[112:115], v[156:159], v[192:195], v[112:115]
	v_mfma_f32_16x16x32_bf16 v[88:91], v[148:151], v[212:215], v[88:91]
	v_mfma_f32_16x16x32_bf16 v[84:87], v[156:159], v[212:215], v[84:87]
	v_mfma_f32_16x16x32_bf16 v[108:111], v[148:151], v[220:223], v[108:111]
	v_mfma_f32_16x16x32_bf16 v[104:107], v[156:159], v[220:223], v[104:107]
	v_mfma_f32_16x16x32_bf16 v[76:79], v[152:155], v[188:191], v[76:79]
	v_mfma_f32_16x16x32_bf16 v[72:75], v[164:167], v[188:191], v[72:75]
	v_mfma_f32_16x16x32_bf16 v[116:119], v[152:155], v[204:207], v[116:119]
	v_mfma_f32_16x16x32_bf16 v[112:115], v[164:167], v[204:207], v[112:115]
	v_mfma_f32_16x16x32_bf16 v[88:91], v[152:155], v[216:219], v[88:91]
	v_mfma_f32_16x16x32_bf16 v[84:87], v[164:167], v[216:219], v[84:87]
	v_mfma_f32_16x16x32_bf16 v[108:111], v[152:155], v[232:235], v[108:111]
	v_mfma_f32_16x16x32_bf16 v[104:107], v[164:167], v[232:235], v[104:107]
	v_mfma_f32_16x16x32_bf16 v[96:99], v[168:171], v[184:187], v[96:99]
	v_mfma_f32_16x16x32_bf16 v[92:95], v[176:179], v[184:187], v[92:95]
	v_mfma_f32_16x16x32_bf16 v[124:127], v[168:171], v[192:195], v[124:127]
	v_mfma_f32_16x16x32_bf16 v[120:123], v[176:179], v[192:195], v[120:123]
	v_mfma_f32_16x16x32_bf16 v[100:103], v[168:171], v[212:215], v[100:103]
	v_mfma_f32_16x16x32_bf16 v[80:83], v[176:179], v[212:215], v[80:83]
	v_mfma_f32_16x16x32_bf16 v[68:71], v[168:171], v[220:223], v[68:71]
	v_mfma_f32_16x16x32_bf16 v[64:67], v[176:179], v[220:223], v[64:67]
	v_mfma_f32_16x16x32_bf16 v[96:99], v[172:175], v[188:191], v[96:99]
	v_mfma_f32_16x16x32_bf16 v[92:95], v[180:183], v[188:191], v[92:95]
	v_mfma_f32_16x16x32_bf16 v[124:127], v[172:175], v[204:207], v[124:127]
	v_mfma_f32_16x16x32_bf16 v[120:123], v[180:183], v[204:207], v[120:123]
	v_mfma_f32_16x16x32_bf16 v[100:103], v[172:175], v[216:219], v[100:103]
	v_mfma_f32_16x16x32_bf16 v[80:83], v[180:183], v[216:219], v[80:83]
	v_mfma_f32_16x16x32_bf16 v[68:71], v[172:175], v[232:235], v[68:71]
	v_mfma_f32_16x16x32_bf16 v[64:67], v[180:183], v[232:235], v[64:67]
	s_barrier
	s_add_i32 s35, s35, s9
	v_lshl_add_u64 v[236:237], v[236:237], 0, s[10:11]
	s_mov_b32 m0, s35
	ds_read_b128 v[184:187], v145 offset:49152
	ds_read_b128 v[188:191], v145 offset:50176
	ds_read_b128 v[192:195], v145 offset:51200
	ds_read_b128 v[204:207], v145 offset:52224
	ds_read_b128 v[212:215], v145 offset:53248
	ds_read_b128 v[216:219], v145 offset:54272
	ds_read_b128 v[220:223], v145 offset:55296
	ds_read_b128 v[232:235], v145 offset:56320
	global_load_lds_dwordx4 v[236:237], off
	s_add_i32 m0, s35, 0x2000
	s_add_u32 s36, s50, 0x40080
	v_lshl_add_u64 v[236:237], v[238:239], 0, s[10:11]
	s_addc_u32 s37, s51, 0
	s_add_i32 s35, s43, s9
	global_load_lds_dwordx4 v[236:237], off
	v_lshl_add_u64 v[236:237], s[36:37], 0, v[196:197]
	s_mov_b32 m0, s35
	s_nop 0
	global_load_lds_dwordx4 v[236:237], off
	v_lshl_add_u64 v[236:237], s[36:37], 0, v[132:133]
	s_add_i32 m0, s35, 0x2000
	s_nop 0
	global_load_lds_dwordx4 v[236:237], off
	v_lshl_add_u64 v[236:237], v[240:241], 0, s[10:11]
	s_mov_b32 m0, s23
	s_nop 0
	global_load_lds_dwordx4 v[236:237], off
	v_lshl_add_u64 v[236:237], v[242:243], 0, s[10:11]
	s_mov_b32 m0, s24
	s_nop 0
	global_load_lds_dwordx4 v[236:237], off
	s_waitcnt vmcnt(8)
	s_waitcnt lgkmcnt(0)
	s_barrier
	s_waitcnt lgkmcnt(0)
	v_mfma_f32_16x16x32_bf16 v[60:63], v[148:151], v[184:187], v[60:63]
	v_mfma_f32_16x16x32_bf16 v[56:59], v[156:159], v[184:187], v[56:59]
	v_mfma_f32_16x16x32_bf16 v[44:47], v[148:151], v[192:195], v[44:47]
	v_mfma_f32_16x16x32_bf16 v[40:43], v[156:159], v[192:195], v[40:43]
	v_mfma_f32_16x16x32_bf16 v[28:31], v[148:151], v[212:215], v[28:31]
	v_mfma_f32_16x16x32_bf16 v[24:27], v[156:159], v[212:215], v[24:27]
	v_mfma_f32_16x16x32_bf16 v[12:15], v[148:151], v[220:223], v[12:15]
	v_mfma_f32_16x16x32_bf16 v[8:11], v[156:159], v[220:223], v[8:11]
	v_mfma_f32_16x16x32_bf16 v[60:63], v[152:155], v[188:191], v[60:63]
	v_mfma_f32_16x16x32_bf16 v[56:59], v[164:167], v[188:191], v[56:59]
	v_mfma_f32_16x16x32_bf16 v[44:47], v[152:155], v[204:207], v[44:47]
	v_mfma_f32_16x16x32_bf16 v[40:43], v[164:167], v[204:207], v[40:43]
	v_mfma_f32_16x16x32_bf16 v[28:31], v[152:155], v[216:219], v[28:31]
	v_mfma_f32_16x16x32_bf16 v[24:27], v[164:167], v[216:219], v[24:27]
	v_mfma_f32_16x16x32_bf16 v[12:15], v[152:155], v[232:235], v[12:15]
	v_mfma_f32_16x16x32_bf16 v[8:11], v[164:167], v[232:235], v[8:11]
	v_mfma_f32_16x16x32_bf16 v[52:55], v[168:171], v[184:187], v[52:55]
	v_mfma_f32_16x16x32_bf16 v[48:51], v[176:179], v[184:187], v[48:51]
	v_mfma_f32_16x16x32_bf16 v[36:39], v[168:171], v[192:195], v[36:39]
	v_mfma_f32_16x16x32_bf16 v[32:35], v[176:179], v[192:195], v[32:35]
	v_mfma_f32_16x16x32_bf16 v[20:23], v[168:171], v[212:215], v[20:23]
	v_mfma_f32_16x16x32_bf16 v[16:19], v[176:179], v[212:215], v[16:19]
	v_mfma_f32_16x16x32_bf16 v[4:7], v[168:171], v[220:223], v[4:7]
	v_mfma_f32_16x16x32_bf16 v[0:3], v[176:179], v[220:223], v[0:3]
	v_mfma_f32_16x16x32_bf16 v[52:55], v[172:175], v[188:191], v[52:55]
	v_mfma_f32_16x16x32_bf16 v[48:51], v[180:183], v[188:191], v[48:51]
	v_mfma_f32_16x16x32_bf16 v[36:39], v[172:175], v[204:207], v[36:39]
	v_mfma_f32_16x16x32_bf16 v[32:35], v[180:183], v[204:207], v[32:35]
	v_mfma_f32_16x16x32_bf16 v[20:23], v[172:175], v[216:219], v[20:23]
	v_mfma_f32_16x16x32_bf16 v[16:19], v[180:183], v[216:219], v[16:19]
	v_mfma_f32_16x16x32_bf16 v[4:7], v[172:175], v[232:235], v[4:7]
	v_mfma_f32_16x16x32_bf16 v[0:3], v[180:183], v[232:235], v[0:3]
	s_add_i32 s34, s34, 2
	s_add_u32 s48, s48, 0x100
	s_addc_u32 s49, s49, 0
	s_add_u32 s35, s12, s48
	s_addc_u32 s36, s13, s49
	s_add_u32 s35, s35, 0x100
	s_addc_u32 s36, s36, 0
	s_add_u32 s37, s27, s48
	s_addc_u32 s43, s28, s49
	s_add_i32 s58, 0, 0x10000
	s_cmpk_eq_i32 s48, 0x700
	s_cselect_b32 s53, s29, s36
	s_cselect_b32 s52, s30, s35
	v_add_u32_e32 v147, s58, v144
	s_cselect_b32 s51, s19, s43
	s_cselect_b32 s50, s31, s37
	s_add_i32 s35, 0, 0x14000
	s_cmp_gt_u32 s34, 13
	s_barrier
	s_cbranch_scc0 .Lrot_lbb0_1033
	s_add_u32 s48, s27, 0xffffff00
	s_addc_u32 s49, s28, -1
	s_andn2_b64 vcc, exec, s[40:41]
	s_cbranch_vccnz .LBB0_1036
	v_mov_b32_e32 v0, 0
	s_mov_b32 s8, s18
	s_mov_b32 s6, s42
	s_mov_b64 s[12:13], s[46:47]
	s_mov_b32 s25, s26
	v_mov_b32_e32 v1, v0
	v_mov_b32_e32 v2, v0
	v_mov_b32_e32 v3, v0
	v_mov_b32_e32 v4, v0
	v_mov_b32_e32 v5, v0
	v_mov_b32_e32 v6, v0
	v_mov_b32_e32 v7, v0
	v_mov_b32_e32 v16, v0
	v_mov_b32_e32 v17, v0
	v_mov_b32_e32 v18, v0
	v_mov_b32_e32 v19, v0
	v_mov_b32_e32 v20, v0
	v_mov_b32_e32 v21, v0
	v_mov_b32_e32 v22, v0
	v_mov_b32_e32 v23, v0
	v_mov_b32_e32 v32, v0
	v_mov_b32_e32 v33, v0
	v_mov_b32_e32 v34, v0
	v_mov_b32_e32 v35, v0
	v_mov_b32_e32 v36, v0
	v_mov_b32_e32 v37, v0
	v_mov_b32_e32 v38, v0
	v_mov_b32_e32 v39, v0
	v_mov_b32_e32 v48, v0
	v_mov_b32_e32 v49, v0
	v_mov_b32_e32 v50, v0
	v_mov_b32_e32 v51, v0
	v_mov_b32_e32 v52, v0
	v_mov_b32_e32 v53, v0
	v_mov_b32_e32 v54, v0
	v_mov_b32_e32 v55, v0
	v_mov_b32_e32 v8, v0
	v_mov_b32_e32 v9, v0
	v_mov_b32_e32 v10, v0
	v_mov_b32_e32 v11, v0
	v_mov_b32_e32 v12, v0
	v_mov_b32_e32 v13, v0
	v_mov_b32_e32 v14, v0
	v_mov_b32_e32 v15, v0
	v_mov_b32_e32 v24, v0
	v_mov_b32_e32 v25, v0
	v_mov_b32_e32 v26, v0
	v_mov_b32_e32 v27, v0
	v_mov_b32_e32 v28, v0
	v_mov_b32_e32 v29, v0
	v_mov_b32_e32 v30, v0
	v_mov_b32_e32 v31, v0
	v_mov_b32_e32 v40, v0
	v_mov_b32_e32 v41, v0
	v_mov_b32_e32 v42, v0
	v_mov_b32_e32 v43, v0
	v_mov_b32_e32 v44, v0
	v_mov_b32_e32 v45, v0
	v_mov_b32_e32 v46, v0
	v_mov_b32_e32 v47, v0
	v_mov_b32_e32 v56, v0
	v_mov_b32_e32 v57, v0
	v_mov_b32_e32 v58, v0
	v_mov_b32_e32 v59, v0
	v_mov_b32_e32 v60, v0
	v_mov_b32_e32 v61, v0
	v_mov_b32_e32 v62, v0
	v_mov_b32_e32 v63, v0
	v_mov_b32_e32 v64, v0
	v_mov_b32_e32 v65, v0
	v_mov_b32_e32 v66, v0
	v_mov_b32_e32 v67, v0
	v_mov_b32_e32 v68, v0
	v_mov_b32_e32 v69, v0
	v_mov_b32_e32 v70, v0
	v_mov_b32_e32 v71, v0
	v_mov_b32_e32 v80, v0
	v_mov_b32_e32 v81, v0
	v_mov_b32_e32 v82, v0
	v_mov_b32_e32 v83, v0
	v_mov_b32_e32 v100, v0
	v_mov_b32_e32 v101, v0
	v_mov_b32_e32 v102, v0
	v_mov_b32_e32 v103, v0
	v_mov_b32_e32 v120, v0
	v_mov_b32_e32 v121, v0
	v_mov_b32_e32 v122, v0
	v_mov_b32_e32 v123, v0
	v_mov_b32_e32 v124, v0
	v_mov_b32_e32 v125, v0
	v_mov_b32_e32 v126, v0
	v_mov_b32_e32 v127, v0
	v_mov_b32_e32 v92, v0
	v_mov_b32_e32 v93, v0
	v_mov_b32_e32 v94, v0
	v_mov_b32_e32 v95, v0
	v_mov_b32_e32 v96, v0
	v_mov_b32_e32 v97, v0
	v_mov_b32_e32 v98, v0
	v_mov_b32_e32 v99, v0
	v_mov_b32_e32 v104, v0
	v_mov_b32_e32 v105, v0
	v_mov_b32_e32 v106, v0
	v_mov_b32_e32 v107, v0
	v_mov_b32_e32 v108, v0
	v_mov_b32_e32 v109, v0
	v_mov_b32_e32 v110, v0
	v_mov_b32_e32 v111, v0
	v_mov_b32_e32 v84, v0
	v_mov_b32_e32 v85, v0
	v_mov_b32_e32 v86, v0
	v_mov_b32_e32 v87, v0
	v_mov_b32_e32 v88, v0
	v_mov_b32_e32 v89, v0
	v_mov_b32_e32 v90, v0
	v_mov_b32_e32 v91, v0
	v_mov_b32_e32 v112, v0
	v_mov_b32_e32 v113, v0
	v_mov_b32_e32 v114, v0
	v_mov_b32_e32 v115, v0
	v_mov_b32_e32 v116, v0
	v_mov_b32_e32 v117, v0
	v_mov_b32_e32 v118, v0
	v_mov_b32_e32 v119, v0
	v_mov_b32_e32 v72, v0
	v_mov_b32_e32 v73, v0
	v_mov_b32_e32 v74, v0
	v_mov_b32_e32 v75, v0
	v_mov_b32_e32 v76, v0
	v_mov_b32_e32 v77, v0
	v_mov_b32_e32 v78, v0
	v_mov_b32_e32 v79, v0
	s_branch .LBB0_1037
